# K-loop: LDS-DMA pair of the 12-read phases (P1,P5) moved from the load segment into the same phase MFMA shadow
# baseline (speedup 1.0000x reference)
; #define PG8_STAGE(bufoff, gbase, voff) do { _Pragma("unroll") for (int _i = 0; _i < 2; ++_i) \
;         __builtin_amdgcn_global_load_lds((const unsigned*)((const char*)(gbase) + (voff)[_i]), (LAS unsigned*)(lds + (bufoff) + ldsw + _i * 8192), 16, 0, 0); } while (0)
; #define PG8_LDA(dst, b, h) do { _Pragma("unroll") for (int m = 0; m < 4; ++m) _Pragma("unroll") for (int k = 0; k < 2; ++k) dst[m][k] = *(const LAS bf16x8*)(lds + PG8_SA(b, h) + aoff + m * 2048 + k * 1024); } while (0)
; #define PG8_LDB(dst, b, h) do { _Pragma("unroll") for (int n = 0; n < 2; ++n) _Pragma("unroll") for (int k = 0; k < 2; ++k) dst[n][k] = *(const LAS bf16x8*)(lds + PG8_SB(b, h) + boff + n * 2048 + k * 1024); } while (0)
; #define PG8_WAIT_V(n) asm volatile("s_waitcnt vmcnt(" #n ")" ::: "memory")
; #define PG8_WAIT_L(n) asm volatile("s_waitcnt lgkmcnt(" #n ")" ::: "memory")
; #define PG8_BAR __builtin_amdgcn_s_barrier()
; #define PG8_SCHED __builtin_amdgcn_sched_barrier(0)
; template <class Epi>
; __device__ __forceinline__ void gemm_phase(LAS unsigned char* lds, const Gemm g, const StaticOrder& S, const Epi& E) {
;     ...
;         for (int t = 0; t < nt; t += 2) {
;             const bool last = (t == nt - 2);
;             const char* a1 = cA + (size_t)(t + 1) * kstep;
;             const char* a2 = last ? nA : cA + (size_t)(t + 2) * kstep; const char* b2 = last ? nB : cB + (size_t)(t + 2) * kstep;
;             const char* a3 = a2 + kstep; const char* b3 = b2 + kstep;
;             PG8_LDB(B0, 0, 0); PG8_SCHED; PG8_LDA(At, 0, 0); PG8_STAGE(PG8_SA(1, 1), a1 + hstepA, voffA);
;             PG8_WAIT_L(8); PG8_BAR; PG8_WAIT_L(0); PG8_MMA(0, 0, At, B0); PG8_BAR; PG8_SCHED;
;             PG8_LDB(B1, 0, 1); PG8_STAGE(PG8_SB(0, 0), b2, voffB);
;             PG8_BAR; PG8_WAIT_L(0); PG8_MMA(0, 1, At, B1); PG8_BAR;
;             PG8_LDA(At, 0, 1); PG8_STAGE(PG8_SA(0, 0), a2, voffA);
;             PG8_BAR; PG8_WAIT_L(0); PG8_MMA(1, 0, At, B0); PG8_BAR; PG8_SCHED;
;             PG8_STAGE(PG8_SB(0, 1), b2 + hstepB, voffB);
;             PG8_WAIT_V(6); PG8_BAR; PG8_MMA(1, 1, At, B1); PG8_BAR;
;             PG8_LDB(B0, 1, 0); PG8_SCHED; PG8_LDA(At, 1, 0); PG8_STAGE(PG8_SA(0, 1), a2 + hstepA, voffA);
;             PG8_WAIT_L(8); PG8_BAR; PG8_WAIT_L(0); PG8_MMA(0, 0, At, B0); PG8_BAR; PG8_SCHED;
.LBB0_140:
	v_mov_b64_e32 v[0:1], 0x800
	s_ashr_i32 s15, s14, 31
	v_cmp_lt_i64_e32 vcc, s[16:17], v[0:1]
	s_lshl_b64 s[16:17], s[14:15], 20
	v_readlane_b32 s18, v252, 53
	v_readlane_b32 s19, v252, 54
	s_add_u32 s16, s18, s16
	s_addc_u32 s17, s19, s17
	s_and_b64 s[18:19], vcc, exec
	s_cselect_b32 s15, s17, s23
	s_cselect_b32 s49, s16, s22
	s_ashr_i32 s5, s4, 31
	s_lshl_b64 s[18:19], s[4:5], 20
	s_add_u32 s18, s34, s18
	s_addc_u32 s19, s35, s19
	s_and_b64 s[26:27], vcc, exec
	s_cselect_b32 s5, s19, s25
	s_cselect_b32 s50, s18, s24
	s_add_u32 s22, s22, 0x84000
	s_addc_u32 s23, s23, 0
	s_add_u32 s51, s24, 0x8000
	s_addc_u32 s52, s25, 0
	s_mov_b32 s54, -2
	s_add_u32 s24, s22, 0xfff84000
	s_addc_u32 s25, s23, -1
	s_cmp_eq_u32 s54, 28
	s_cselect_b32 s28, s49, s24
	s_cselect_b32 s29, s15, s25
	s_cselect_b32 s24, s50, s51
	s_cselect_b32 s25, s5, s52
	s_add_u32 s26, s28, 0x4000
	s_addc_u32 s27, s29, 0
	s_add_i32 s55, 0, 0x10000
	v_add_u32_e32 v148, s55, v134
	ds_read_b128 v[136:139], v148
	ds_read_b128 v[140:143], v148 offset:1024
	ds_read_b128 v[144:147], v148 offset:2048
	ds_read_b128 v[148:151], v148 offset:3072
	ds_read_b128 v[156:159], v135
	ds_read_b128 v[160:163], v135 offset:1024
	ds_read_b128 v[164:167], v135 offset:2048
	ds_read_b128 v[168:171], v135 offset:3072
	ds_read_b128 v[172:175], v135 offset:4096
	ds_read_b128 v[176:179], v135 offset:5120
	ds_read_b128 v[180:183], v135 offset:6144
	ds_read_b128 v[184:187], v135 offset:7168
	s_waitcnt lgkmcnt(8)
	s_barrier
	s_waitcnt lgkmcnt(0)
	v_mfma_f32_16x16x32_bf16 v[124:127], v[136:139], v[156:159], 0
	s_setprio 1
	v_mfma_f32_16x16x32_bf16 v[120:123], v[144:147], v[156:159], 0
	v_mfma_f32_16x16x32_bf16 v[108:111], v[136:139], v[164:167], 0
	s_add_i32 m0, s37, 0xc000
	v_lshl_add_u64 v[188:189], s[22:23], 0, v[128:129]
	global_load_lds_dwordx4 v[188:189], off
	v_mfma_f32_16x16x32_bf16 v[104:107], v[144:147], v[164:167], 0
	v_mfma_f32_16x16x32_bf16 v[92:95], v[136:139], v[172:175], 0
	v_mfma_f32_16x16x32_bf16 v[88:91], v[144:147], v[172:175], 0
	v_mfma_f32_16x16x32_bf16 v[76:79], v[136:139], v[180:183], 0
	s_add_i32 m0, s37, 0xe000
	v_lshl_add_u64 v[188:189], s[22:23], 0, v[130:131]
	global_load_lds_dwordx4 v[188:189], off
	v_mfma_f32_16x16x32_bf16 v[72:75], v[144:147], v[180:183], 0
	v_mfma_f32_16x16x32_bf16 v[124:127], v[140:143], v[160:163], v[124:127]
	v_mfma_f32_16x16x32_bf16 v[120:123], v[148:151], v[160:163], v[120:123]
	v_mfma_f32_16x16x32_bf16 v[108:111], v[140:143], v[168:171], v[108:111]
	v_mfma_f32_16x16x32_bf16 v[104:107], v[148:151], v[168:171], v[104:107]
	v_mfma_f32_16x16x32_bf16 v[92:95], v[140:143], v[176:179], v[92:95]
	v_mfma_f32_16x16x32_bf16 v[88:91], v[148:151], v[176:179], v[88:91]
	v_mfma_f32_16x16x32_bf16 v[76:79], v[140:143], v[184:187], v[76:79]
	s_setprio 0
	v_mfma_f32_16x16x32_bf16 v[72:75], v[148:151], v[184:187], v[72:75]
	s_barrier
	s_add_i32 s58, 0, 0x14000
	s_add_i32 s55, s55, s36
	v_add_u32_e32 v152, s58, v134
	v_lshl_add_u64 v[204:205], s[24:25], 0, v[128:129]
	s_mov_b32 m0, s55
	ds_read_b128 v[188:191], v152
	ds_read_b128 v[192:195], v152 offset:1024
	ds_read_b128 v[196:199], v152 offset:2048
	ds_read_b128 v[200:203], v152 offset:3072
	global_load_lds_dwordx4 v[204:205], off
	s_add_i32 m0, s55, 0x2000
	v_lshl_add_u64 v[204:205], s[24:25], 0, v[130:131]
	global_load_lds_dwordx4 v[204:205], off
	s_barrier
	s_waitcnt lgkmcnt(0)
	v_mfma_f32_16x16x32_bf16 v[116:119], v[188:191], v[156:159], 0
	s_setprio 1
	v_mfma_f32_16x16x32_bf16 v[112:115], v[196:199], v[156:159], 0
	s_mov_b32 m0, s37
	v_lshl_add_u64 v[204:205], s[28:29], 0, v[128:129]
	v_mfma_f32_16x16x32_bf16 v[100:103], v[188:191], v[164:167], 0
	v_mfma_f32_16x16x32_bf16 v[96:99], v[196:199], v[164:167], 0
	v_mfma_f32_16x16x32_bf16 v[84:87], v[188:191], v[172:175], 0
	v_mfma_f32_16x16x32_bf16 v[80:83], v[196:199], v[172:175], 0
	v_mfma_f32_16x16x32_bf16 v[68:71], v[188:191], v[180:183], 0
	v_mfma_f32_16x16x32_bf16 v[64:67], v[196:199], v[180:183], 0
	v_mfma_f32_16x16x32_bf16 v[116:119], v[192:195], v[160:163], v[116:119]
	v_mfma_f32_16x16x32_bf16 v[112:115], v[200:203], v[160:163], v[112:115]
	v_mfma_f32_16x16x32_bf16 v[100:103], v[192:195], v[168:171], v[100:103]
	v_mfma_f32_16x16x32_bf16 v[96:99], v[200:203], v[168:171], v[96:99]
	v_mfma_f32_16x16x32_bf16 v[84:87], v[192:195], v[176:179], v[84:87]
	v_mfma_f32_16x16x32_bf16 v[80:83], v[200:203], v[176:179], v[80:83]
	v_mfma_f32_16x16x32_bf16 v[68:71], v[192:195], v[184:187], v[68:71]
	s_setprio 0
	v_mfma_f32_16x16x32_bf16 v[64:67], v[200:203], v[184:187], v[64:67]
	s_barrier
	ds_read_b128 v[156:159], v135 offset:16384
	ds_read_b128 v[160:163], v135 offset:17408
	ds_read_b128 v[164:167], v135 offset:18432
	ds_read_b128 v[168:171], v135 offset:19456
	ds_read_b128 v[172:175], v135 offset:20480
	ds_read_b128 v[176:179], v135 offset:21504
	ds_read_b128 v[180:183], v135 offset:22528
	ds_read_b128 v[184:187], v135 offset:23552
	global_load_lds_dwordx4 v[204:205], off
	s_mov_b32 m0, s38
	v_lshl_add_u64 v[204:205], s[28:29], 0, v[130:131]
	global_load_lds_dwordx4 v[204:205], off
	s_barrier
	s_waitcnt lgkmcnt(0)
	v_mfma_f32_16x16x32_bf16 v[60:63], v[136:139], v[156:159], 0
	s_setprio 1
	v_mfma_f32_16x16x32_bf16 v[56:59], v[144:147], v[156:159], 0
	v_mfma_f32_16x16x32_bf16 v[44:47], v[136:139], v[164:167], 0
	v_mfma_f32_16x16x32_bf16 v[40:43], v[144:147], v[164:167], 0
	v_mfma_f32_16x16x32_bf16 v[28:31], v[136:139], v[172:175], 0
	v_mfma_f32_16x16x32_bf16 v[24:27], v[144:147], v[172:175], 0
	v_mfma_f32_16x16x32_bf16 v[12:15], v[136:139], v[180:183], 0
	v_mfma_f32_16x16x32_bf16 v[8:11], v[144:147], v[180:183], 0
	v_mfma_f32_16x16x32_bf16 v[60:63], v[140:143], v[160:163], v[60:63]
	v_mfma_f32_16x16x32_bf16 v[56:59], v[148:151], v[160:163], v[56:59]
	v_mfma_f32_16x16x32_bf16 v[44:47], v[140:143], v[168:171], v[44:47]
	v_mfma_f32_16x16x32_bf16 v[40:43], v[148:151], v[168:171], v[40:43]
	v_mfma_f32_16x16x32_bf16 v[28:31], v[140:143], v[176:179], v[28:31]
	v_mfma_f32_16x16x32_bf16 v[24:27], v[148:151], v[176:179], v[24:27]
	v_mfma_f32_16x16x32_bf16 v[12:15], v[140:143], v[184:187], v[12:15]
	s_setprio 0
	v_mfma_f32_16x16x32_bf16 v[8:11], v[148:151], v[184:187], v[8:11]
	s_barrier
; #define PG8_STAGE(bufoff, gbase, voff) do { _Pragma("unroll") for (int _i = 0; _i < 2; ++_i) \
;         __builtin_amdgcn_global_load_lds((const unsigned*)((const char*)(gbase) + (voff)[_i]), (LAS unsigned*)(lds + (bufoff) + ldsw + _i * 8192), 16, 0, 0); } while (0)
; #define PG8_LDA(dst, b, h) do { _Pragma("unroll") for (int m = 0; m < 4; ++m) _Pragma("unroll") for (int k = 0; k < 2; ++k) dst[m][k] = *(const LAS bf16x8*)(lds + PG8_SA(b, h) + aoff + m * 2048 + k * 1024); } while (0)
; #define PG8_LDB(dst, b, h) do { _Pragma("unroll") for (int n = 0; n < 2; ++n) _Pragma("unroll") for (int k = 0; k < 2; ++k) dst[n][k] = *(const LAS bf16x8*)(lds + PG8_SB(b, h) + boff + n * 2048 + k * 1024); } while (0)
; #define PG8_MMA(ai, bj, At, Bt) do { __builtin_amdgcn_s_setprio(1); _Pragma("unroll") for (int m = 0; m < 4; ++m) _Pragma("unroll") for (int n = 0; n < 2; ++n) _Pragma("unroll") for (int k = 0; k < 2; ++k) \
;         acc[ai][bj][m][n] = __builtin_amdgcn_mfma_f32_16x16x32_bf16(Bt[n][k], At[m][k], acc[ai][bj][m][n], 0, 0, 0); __builtin_amdgcn_s_setprio(0); } while (0)
; #define PG8_WAIT_V(n) asm volatile("s_waitcnt vmcnt(" #n ")" ::: "memory")
; #define PG8_WAIT_L(n) asm volatile("s_waitcnt lgkmcnt(" #n ")" ::: "memory")
; #define PG8_BAR __builtin_amdgcn_s_barrier()
; #define PG8_SCHED __builtin_amdgcn_sched_barrier(0)
; template <class Epi>
; __device__ __forceinline__ void gemm_phase(LAS unsigned char* lds, const Gemm g, const StaticOrder& S, const Epi& E) {
;     ...
;             PG8_STAGE(PG8_SB(0, 1), b2 + hstepB, voffB);
;             PG8_WAIT_V(6); PG8_BAR; PG8_MMA(1, 1, At, B1); PG8_BAR;
;             PG8_LDB(B0, 1, 0); PG8_SCHED; PG8_LDA(At, 1, 0); PG8_STAGE(PG8_SA(0, 1), a2 + hstepA, voffA);
;             PG8_WAIT_L(8); PG8_BAR; PG8_WAIT_L(0); PG8_MMA(0, 0, At, B0); PG8_BAR; PG8_SCHED;
;             PG8_LDB(B1, 1, 1); PG8_STAGE(PG8_SB(1, 0), b3, voffB);
;             PG8_BAR; PG8_WAIT_L(0); PG8_MMA(0, 1, At, B1); PG8_BAR;
;             PG8_LDA(At, 1, 1); PG8_STAGE(PG8_SA(1, 0), a3, voffA);
;             PG8_BAR; PG8_WAIT_L(0); PG8_MMA(1, 0, At, B0); PG8_BAR; PG8_SCHED;
	s_add_u32 s56, s24, 0x80000
	s_addc_u32 s57, s25, 0
	s_add_i32 s55, s58, s36
	s_mov_b32 m0, s55
	v_lshl_add_u64 v[136:137], s[56:57], 0, v[128:129]
	global_load_lds_dwordx4 v[136:137], off
	s_add_i32 m0, s55, 0x2000
	v_lshl_add_u64 v[136:137], s[56:57], 0, v[130:131]
	global_load_lds_dwordx4 v[136:137], off
	s_waitcnt vmcnt(6)
	s_barrier
	v_mfma_f32_16x16x32_bf16 v[52:55], v[188:191], v[156:159], 0
	s_setprio 1
	v_mfma_f32_16x16x32_bf16 v[48:51], v[196:199], v[156:159], 0
	s_add_i32 s55, 0, 0x18000
	v_add_u32_e32 v148, s55, v134
	v_mfma_f32_16x16x32_bf16 v[36:39], v[188:191], v[164:167], 0
	v_mfma_f32_16x16x32_bf16 v[32:35], v[196:199], v[164:167], 0
	v_mfma_f32_16x16x32_bf16 v[20:23], v[188:191], v[172:175], 0
	v_mfma_f32_16x16x32_bf16 v[16:19], v[196:199], v[172:175], 0
	v_mfma_f32_16x16x32_bf16 v[4:7], v[188:191], v[180:183], 0
	v_mfma_f32_16x16x32_bf16 v[0:3], v[196:199], v[180:183], 0
	v_mfma_f32_16x16x32_bf16 v[52:55], v[192:195], v[160:163], v[52:55]
	v_mfma_f32_16x16x32_bf16 v[48:51], v[200:203], v[160:163], v[48:51]
	v_mfma_f32_16x16x32_bf16 v[36:39], v[192:195], v[168:171], v[36:39]
	v_mfma_f32_16x16x32_bf16 v[32:35], v[200:203], v[168:171], v[32:35]
	v_mfma_f32_16x16x32_bf16 v[20:23], v[192:195], v[176:179], v[20:23]
	v_mfma_f32_16x16x32_bf16 v[16:19], v[200:203], v[176:179], v[16:19]
	v_mfma_f32_16x16x32_bf16 v[4:7], v[192:195], v[184:187], v[4:7]
	s_setprio 0
	v_mfma_f32_16x16x32_bf16 v[0:3], v[200:203], v[184:187], v[0:3]
	s_barrier
	ds_read_b128 v[136:139], v148
	ds_read_b128 v[140:143], v148 offset:1024
	ds_read_b128 v[144:147], v148 offset:2048
	ds_read_b128 v[148:151], v148 offset:3072
	s_add_u32 s28, s28, 0x80000
	s_addc_u32 s29, s29, 0
	ds_read_b128 v[156:159], v135 offset:32768
	ds_read_b128 v[160:163], v135 offset:33792
	ds_read_b128 v[164:167], v135 offset:34816
	ds_read_b128 v[168:171], v135 offset:35840
	ds_read_b128 v[172:175], v135 offset:36864
	ds_read_b128 v[176:179], v135 offset:37888
	ds_read_b128 v[180:183], v135 offset:38912
	ds_read_b128 v[184:187], v135 offset:39936
	s_waitcnt lgkmcnt(8)
	s_barrier
	s_waitcnt lgkmcnt(0)
	v_mfma_f32_16x16x32_bf16 v[124:127], v[136:139], v[156:159], v[124:127]
	s_setprio 1
	v_mfma_f32_16x16x32_bf16 v[120:123], v[144:147], v[156:159], v[120:123]
	v_mfma_f32_16x16x32_bf16 v[108:111], v[136:139], v[164:167], v[108:111]
	s_mov_b32 m0, s39
	v_lshl_add_u64 v[188:189], s[28:29], 0, v[128:129]
	global_load_lds_dwordx4 v[188:189], off
	v_mfma_f32_16x16x32_bf16 v[104:107], v[144:147], v[164:167], v[104:107]
	v_mfma_f32_16x16x32_bf16 v[92:95], v[136:139], v[172:175], v[92:95]
	v_mfma_f32_16x16x32_bf16 v[88:91], v[144:147], v[172:175], v[88:91]
	v_mfma_f32_16x16x32_bf16 v[76:79], v[136:139], v[180:183], v[76:79]
	s_mov_b32 m0, s40
	v_lshl_add_u64 v[188:189], s[28:29], 0, v[130:131]
	global_load_lds_dwordx4 v[188:189], off
	v_mfma_f32_16x16x32_bf16 v[72:75], v[144:147], v[180:183], v[72:75]
	v_mfma_f32_16x16x32_bf16 v[124:127], v[140:143], v[160:163], v[124:127]
	v_mfma_f32_16x16x32_bf16 v[120:123], v[148:151], v[160:163], v[120:123]
	v_mfma_f32_16x16x32_bf16 v[108:111], v[140:143], v[168:171], v[108:111]
	v_mfma_f32_16x16x32_bf16 v[104:107], v[148:151], v[168:171], v[104:107]
	v_mfma_f32_16x16x32_bf16 v[92:95], v[140:143], v[176:179], v[92:95]
	v_mfma_f32_16x16x32_bf16 v[88:91], v[148:151], v[176:179], v[88:91]
	v_mfma_f32_16x16x32_bf16 v[76:79], v[140:143], v[184:187], v[76:79]
	s_setprio 0
	v_mfma_f32_16x16x32_bf16 v[72:75], v[148:151], v[184:187], v[72:75]
	s_barrier
	s_add_i32 s56, 0, 0x1c000
	s_add_u32 s28, s24, 0x4000
	s_addc_u32 s29, s25, 0
	s_add_i32 s55, s55, s36
	v_add_u32_e32 v152, s56, v134
	v_lshl_add_u64 v[204:205], s[28:29], 0, v[128:129]
	s_mov_b32 m0, s55
	ds_read_b128 v[188:191], v152
	ds_read_b128 v[192:195], v152 offset:1024
	ds_read_b128 v[196:199], v152 offset:2048
	ds_read_b128 v[200:203], v152 offset:3072
	global_load_lds_dwordx4 v[204:205], off
	s_add_i32 m0, s55, 0x2000
	v_lshl_add_u64 v[204:205], s[28:29], 0, v[130:131]
	global_load_lds_dwordx4 v[204:205], off
	s_barrier
	s_waitcnt lgkmcnt(0)
	v_mfma_f32_16x16x32_bf16 v[116:119], v[188:191], v[156:159], v[116:119]
	s_setprio 1
	v_mfma_f32_16x16x32_bf16 v[112:115], v[196:199], v[156:159], v[112:115]
	s_mov_b32 m0, s43
	v_lshl_add_u64 v[204:205], s[26:27], 0, v[128:129]
	v_mfma_f32_16x16x32_bf16 v[100:103], v[188:191], v[164:167], v[100:103]
	v_mfma_f32_16x16x32_bf16 v[96:99], v[196:199], v[164:167], v[96:99]
	v_mfma_f32_16x16x32_bf16 v[84:87], v[188:191], v[172:175], v[84:87]
	v_mfma_f32_16x16x32_bf16 v[80:83], v[196:199], v[172:175], v[80:83]
	v_mfma_f32_16x16x32_bf16 v[68:71], v[188:191], v[180:183], v[68:71]
	v_mfma_f32_16x16x32_bf16 v[64:67], v[196:199], v[180:183], v[64:67]
	v_mfma_f32_16x16x32_bf16 v[116:119], v[192:195], v[160:163], v[116:119]
	v_mfma_f32_16x16x32_bf16 v[112:115], v[200:203], v[160:163], v[112:115]
	v_mfma_f32_16x16x32_bf16 v[100:103], v[192:195], v[168:171], v[100:103]
	v_mfma_f32_16x16x32_bf16 v[96:99], v[200:203], v[168:171], v[96:99]
	v_mfma_f32_16x16x32_bf16 v[84:87], v[192:195], v[176:179], v[84:87]
	v_mfma_f32_16x16x32_bf16 v[80:83], v[200:203], v[176:179], v[80:83]
	v_mfma_f32_16x16x32_bf16 v[68:71], v[192:195], v[184:187], v[68:71]
	s_setprio 0
	v_mfma_f32_16x16x32_bf16 v[64:67], v[200:203], v[184:187], v[64:67]
	s_barrier
	ds_read_b128 v[156:159], v135 offset:49152
	ds_read_b128 v[160:163], v135 offset:50176
	ds_read_b128 v[164:167], v135 offset:51200
	ds_read_b128 v[168:171], v135 offset:52224
	ds_read_b128 v[172:175], v135 offset:53248
	ds_read_b128 v[176:179], v135 offset:54272
	ds_read_b128 v[180:183], v135 offset:55296
	ds_read_b128 v[184:187], v135 offset:56320
	global_load_lds_dwordx4 v[204:205], off
	s_mov_b32 m0, s44
	v_lshl_add_u64 v[204:205], s[26:27], 0, v[130:131]
	global_load_lds_dwordx4 v[204:205], off
	s_barrier
; #define PG8_STAGE(bufoff, gbase, voff) do { _Pragma("unroll") for (int _i = 0; _i < 2; ++_i) \
;         __builtin_amdgcn_global_load_lds((const unsigned*)((const char*)(gbase) + (voff)[_i]), (LAS unsigned*)(lds + (bufoff) + ldsw + _i * 8192), 16, 0, 0); } while (0)
; #define PG8_LDA(dst, b, h) do { _Pragma("unroll") for (int m = 0; m < 4; ++m) _Pragma("unroll") for (int k = 0; k < 2; ++k) dst[m][k] = *(const LAS bf16x8*)(lds + PG8_SA(b, h) + aoff + m * 2048 + k * 1024); } while (0)
; #define PG8_LDB(dst, b, h) do { _Pragma("unroll") for (int n = 0; n < 2; ++n) _Pragma("unroll") for (int k = 0; k < 2; ++k) dst[n][k] = *(const LAS bf16x8*)(lds + PG8_SB(b, h) + boff + n * 2048 + k * 1024); } while (0)
; #define PG8_MMA(ai, bj, At, Bt) do { __builtin_amdgcn_s_setprio(1); _Pragma("unroll") for (int m = 0; m < 4; ++m) _Pragma("unroll") for (int n = 0; n < 2; ++n) _Pragma("unroll") for (int k = 0; k < 2; ++k) \
;         acc[ai][bj][m][n] = __builtin_amdgcn_mfma_f32_16x16x32_bf16(Bt[n][k], At[m][k], acc[ai][bj][m][n], 0, 0, 0); __builtin_amdgcn_s_setprio(0); } while (0)
; #define PG8_WAIT_V(n) asm volatile("s_waitcnt vmcnt(" #n ")" ::: "memory")
; #define PG8_WAIT_L(n) asm volatile("s_waitcnt lgkmcnt(" #n ")" ::: "memory")
; template <class Epi>
; __device__ __forceinline__ void gemm_phase(LAS unsigned char* lds, const Gemm g, const StaticOrder& S, const Epi& E) {
;     ...
;             const bool last = (t == nt - 2);
;             const char* a1 = cA + (size_t)(t + 1) * kstep;
;             const char* a2 = last ? nA : cA + (size_t)(t + 2) * kstep; const char* b2 = last ? nB : cB + (size_t)(t + 2) * kstep;
;             const char* a3 = a2 + kstep; const char* b3 = b2 + kstep;
;             PG8_LDB(B0, 0, 0); PG8_SCHED; PG8_LDA(At, 0, 0); PG8_STAGE(PG8_SA(1, 1), a1 + hstepA, voffA);
;             PG8_WAIT_L(8); PG8_BAR; PG8_WAIT_L(0); PG8_MMA(0, 0, At, B0); PG8_BAR; PG8_SCHED;
;             PG8_LDB(B1, 0, 1); PG8_STAGE(PG8_SB(0, 0), b2, voffB);
;             PG8_BAR; PG8_WAIT_L(0); PG8_MMA(0, 1, At, B1); PG8_BAR;
;     ...
;             PG8_BAR; PG8_WAIT_L(0); PG8_MMA(0, 1, At, B1); PG8_BAR;
;             PG8_LDA(At, 1, 1); PG8_STAGE(PG8_SA(1, 0), a3, voffA);
;             PG8_BAR; PG8_WAIT_L(0); PG8_MMA(1, 0, At, B0); PG8_BAR; PG8_SCHED;
;             PG8_STAGE(PG8_SB(1, 1), b3 + hstepB, voffB);
;             PG8_WAIT_V(6); PG8_BAR; PG8_MMA(1, 1, At, B1); PG8_BAR;
;         }
	s_waitcnt lgkmcnt(0)
	v_mfma_f32_16x16x32_bf16 v[60:63], v[136:139], v[156:159], v[60:63]
	s_setprio 1
	v_mfma_f32_16x16x32_bf16 v[56:59], v[144:147], v[156:159], v[56:59]
	v_mfma_f32_16x16x32_bf16 v[44:47], v[136:139], v[164:167], v[44:47]
	v_mfma_f32_16x16x32_bf16 v[40:43], v[144:147], v[164:167], v[40:43]
	v_mfma_f32_16x16x32_bf16 v[28:31], v[136:139], v[172:175], v[28:31]
	v_mfma_f32_16x16x32_bf16 v[24:27], v[144:147], v[172:175], v[24:27]
	v_mfma_f32_16x16x32_bf16 v[12:15], v[136:139], v[180:183], v[12:15]
	v_mfma_f32_16x16x32_bf16 v[8:11], v[144:147], v[180:183], v[8:11]
	v_mfma_f32_16x16x32_bf16 v[60:63], v[140:143], v[160:163], v[60:63]
	v_mfma_f32_16x16x32_bf16 v[56:59], v[148:151], v[160:163], v[56:59]
	v_mfma_f32_16x16x32_bf16 v[44:47], v[140:143], v[168:171], v[44:47]
	v_mfma_f32_16x16x32_bf16 v[40:43], v[148:151], v[168:171], v[40:43]
	v_mfma_f32_16x16x32_bf16 v[28:31], v[140:143], v[176:179], v[28:31]
	v_mfma_f32_16x16x32_bf16 v[24:27], v[148:151], v[176:179], v[24:27]
	v_mfma_f32_16x16x32_bf16 v[12:15], v[140:143], v[184:187], v[12:15]
	s_setprio 0
	v_mfma_f32_16x16x32_bf16 v[8:11], v[148:151], v[184:187], v[8:11]
	s_barrier
	s_add_u32 s24, s24, 0x84000
	s_addc_u32 s25, s25, 0
	s_add_i32 s26, s56, s36
	s_mov_b32 m0, s26
	v_lshl_add_u64 v[136:137], s[24:25], 0, v[128:129]
	global_load_lds_dwordx4 v[136:137], off
	s_add_i32 m0, s26, 0x2000
	v_lshl_add_u64 v[136:137], s[24:25], 0, v[130:131]
	global_load_lds_dwordx4 v[136:137], off
	s_waitcnt vmcnt(6)
	s_barrier
	v_mfma_f32_16x16x32_bf16 v[52:55], v[188:191], v[156:159], v[52:55]
	s_setprio 1
	v_mfma_f32_16x16x32_bf16 v[48:51], v[196:199], v[156:159], v[48:51]
	s_add_i32 s54, s54, 2
	s_add_u32 s22, s22, 0x8000
	s_addc_u32 s23, s23, 0
	s_add_u32 s51, s51, 0x8000
	s_addc_u32 s52, s52, 0
	v_mfma_f32_16x16x32_bf16 v[36:39], v[188:191], v[164:167], v[36:39]
	v_mfma_f32_16x16x32_bf16 v[32:35], v[196:199], v[164:167], v[32:35]
	v_mfma_f32_16x16x32_bf16 v[20:23], v[188:191], v[172:175], v[20:23]
	v_mfma_f32_16x16x32_bf16 v[16:19], v[196:199], v[172:175], v[16:19]
	v_mfma_f32_16x16x32_bf16 v[4:7], v[188:191], v[180:183], v[4:7]
	v_mfma_f32_16x16x32_bf16 v[0:3], v[196:199], v[180:183], v[0:3]
	v_mfma_f32_16x16x32_bf16 v[52:55], v[192:195], v[160:163], v[52:55]
	v_mfma_f32_16x16x32_bf16 v[48:51], v[200:203], v[160:163], v[48:51]
	v_mfma_f32_16x16x32_bf16 v[36:39], v[192:195], v[168:171], v[36:39]
	v_mfma_f32_16x16x32_bf16 v[32:35], v[200:203], v[168:171], v[32:35]
	v_mfma_f32_16x16x32_bf16 v[20:23], v[192:195], v[176:179], v[20:23]
	v_mfma_f32_16x16x32_bf16 v[16:19], v[200:203], v[176:179], v[16:19]
	v_mfma_f32_16x16x32_bf16 v[4:7], v[192:195], v[184:187], v[4:7]
	s_cmp_gt_u32 s54, 29
	s_setprio 0
	v_mfma_f32_16x16x32_bf16 v[0:3], v[200:203], v[184:187], v[0:3]
	s_barrier
	s_cbranch_scc0 .LBB0_141
	s_branch .Lpeel_done_141
.LBB0_141:
	s_add_u32 s24, s22, 0xfff84000
	s_addc_u32 s25, s23, -1
	s_cmp_eq_u32 s54, 28
	s_cselect_b32 s28, s49, s24
	s_cselect_b32 s29, s15, s25
	s_cselect_b32 s24, s50, s51
	s_cselect_b32 s25, s5, s52
	s_add_u32 s26, s28, 0x4000
	s_addc_u32 s27, s29, 0
	s_add_i32 s55, 0, 0x10000
	v_add_u32_e32 v148, s55, v134
	ds_read_b128 v[136:139], v148
	ds_read_b128 v[140:143], v148 offset:1024
	ds_read_b128 v[144:147], v148 offset:2048
	ds_read_b128 v[148:151], v148 offset:3072
	ds_read_b128 v[156:159], v135
	ds_read_b128 v[160:163], v135 offset:1024
	ds_read_b128 v[164:167], v135 offset:2048
	ds_read_b128 v[168:171], v135 offset:3072
	ds_read_b128 v[172:175], v135 offset:4096
	ds_read_b128 v[176:179], v135 offset:5120
	ds_read_b128 v[180:183], v135 offset:6144
	ds_read_b128 v[184:187], v135 offset:7168
	s_waitcnt lgkmcnt(8)
	s_barrier
	s_waitcnt lgkmcnt(0)
	v_mfma_f32_16x16x32_bf16 v[124:127], v[136:139], v[156:159], v[124:127]
	s_setprio 1
	v_mfma_f32_16x16x32_bf16 v[120:123], v[144:147], v[156:159], v[120:123]
	v_mfma_f32_16x16x32_bf16 v[108:111], v[136:139], v[164:167], v[108:111]
	s_add_i32 m0, s37, 0xc000
	v_lshl_add_u64 v[188:189], s[22:23], 0, v[128:129]
	global_load_lds_dwordx4 v[188:189], off
	v_mfma_f32_16x16x32_bf16 v[104:107], v[144:147], v[164:167], v[104:107]
	v_mfma_f32_16x16x32_bf16 v[92:95], v[136:139], v[172:175], v[92:95]
	v_mfma_f32_16x16x32_bf16 v[88:91], v[144:147], v[172:175], v[88:91]
	v_mfma_f32_16x16x32_bf16 v[76:79], v[136:139], v[180:183], v[76:79]
	s_add_i32 m0, s37, 0xe000
	v_lshl_add_u64 v[188:189], s[22:23], 0, v[130:131]
	global_load_lds_dwordx4 v[188:189], off
	v_mfma_f32_16x16x32_bf16 v[72:75], v[144:147], v[180:183], v[72:75]
	v_mfma_f32_16x16x32_bf16 v[124:127], v[140:143], v[160:163], v[124:127]
	v_mfma_f32_16x16x32_bf16 v[120:123], v[148:151], v[160:163], v[120:123]
	v_mfma_f32_16x16x32_bf16 v[108:111], v[140:143], v[168:171], v[108:111]
	v_mfma_f32_16x16x32_bf16 v[104:107], v[148:151], v[168:171], v[104:107]
	v_mfma_f32_16x16x32_bf16 v[92:95], v[140:143], v[176:179], v[92:95]
	v_mfma_f32_16x16x32_bf16 v[88:91], v[148:151], v[176:179], v[88:91]
	v_mfma_f32_16x16x32_bf16 v[76:79], v[140:143], v[184:187], v[76:79]
	s_setprio 0
	v_mfma_f32_16x16x32_bf16 v[72:75], v[148:151], v[184:187], v[72:75]
	s_barrier
	s_add_i32 s58, 0, 0x14000
	s_add_i32 s55, s55, s36
	v_add_u32_e32 v152, s58, v134
	v_lshl_add_u64 v[204:205], s[24:25], 0, v[128:129]
	s_mov_b32 m0, s55
	ds_read_b128 v[188:191], v152
	ds_read_b128 v[192:195], v152 offset:1024
	ds_read_b128 v[196:199], v152 offset:2048
	ds_read_b128 v[200:203], v152 offset:3072
	global_load_lds_dwordx4 v[204:205], off
	s_add_i32 m0, s55, 0x2000
	v_lshl_add_u64 v[204:205], s[24:25], 0, v[130:131]
	global_load_lds_dwordx4 v[204:205], off
	s_barrier
; #define PG8_STAGE(bufoff, gbase, voff) do { _Pragma("unroll") for (int _i = 0; _i < 2; ++_i) \
;         __builtin_amdgcn_global_load_lds((const unsigned*)((const char*)(gbase) + (voff)[_i]), (LAS unsigned*)(lds + (bufoff) + ldsw + _i * 8192), 16, 0, 0); } while (0)
; #define PG8_LDA(dst, b, h) do { _Pragma("unroll") for (int m = 0; m < 4; ++m) _Pragma("unroll") for (int k = 0; k < 2; ++k) dst[m][k] = *(const LAS bf16x8*)(lds + PG8_SA(b, h) + aoff + m * 2048 + k * 1024); } while (0)
; #define PG8_LDB(dst, b, h) do { _Pragma("unroll") for (int n = 0; n < 2; ++n) _Pragma("unroll") for (int k = 0; k < 2; ++k) dst[n][k] = *(const LAS bf16x8*)(lds + PG8_SB(b, h) + boff + n * 2048 + k * 1024); } while (0)
; #define PG8_MMA(ai, bj, At, Bt) do { __builtin_amdgcn_s_setprio(1); _Pragma("unroll") for (int m = 0; m < 4; ++m) _Pragma("unroll") for (int n = 0; n < 2; ++n) _Pragma("unroll") for (int k = 0; k < 2; ++k) \
;         acc[ai][bj][m][n] = __builtin_amdgcn_mfma_f32_16x16x32_bf16(Bt[n][k], At[m][k], acc[ai][bj][m][n], 0, 0, 0); __builtin_amdgcn_s_setprio(0); } while (0)
; #define PG8_WAIT_V(n) asm volatile("s_waitcnt vmcnt(" #n ")" ::: "memory")
; #define PG8_WAIT_L(n) asm volatile("s_waitcnt lgkmcnt(" #n ")" ::: "memory")
; #define PG8_BAR __builtin_amdgcn_s_barrier()
; #define PG8_SCHED __builtin_amdgcn_sched_barrier(0)
; template <class Epi>
; __device__ __forceinline__ void gemm_phase(LAS unsigned char* lds, const Gemm g, const StaticOrder& S, const Epi& E) {
;     ...
;             PG8_BAR; PG8_WAIT_L(0); PG8_MMA(0, 1, At, B1); PG8_BAR;
;             PG8_LDA(At, 0, 1); PG8_STAGE(PG8_SA(0, 0), a2, voffA);
;             PG8_BAR; PG8_WAIT_L(0); PG8_MMA(1, 0, At, B0); PG8_BAR; PG8_SCHED;
;             PG8_STAGE(PG8_SB(0, 1), b2 + hstepB, voffB);
;             PG8_WAIT_V(6); PG8_BAR; PG8_MMA(1, 1, At, B1); PG8_BAR;
;             PG8_LDB(B0, 1, 0); PG8_SCHED; PG8_LDA(At, 1, 0); PG8_STAGE(PG8_SA(0, 1), a2 + hstepA, voffA);
;             PG8_WAIT_L(8); PG8_BAR; PG8_WAIT_L(0); PG8_MMA(0, 0, At, B0); PG8_BAR; PG8_SCHED;
;             PG8_LDB(B1, 1, 1); PG8_STAGE(PG8_SB(1, 0), b3, voffB);
;             PG8_BAR; PG8_WAIT_L(0); PG8_MMA(0, 1, At, B1); PG8_BAR;
;             PG8_LDA(At, 1, 1); PG8_STAGE(PG8_SA(1, 0), a3, voffA);
	s_waitcnt lgkmcnt(0)
	v_mfma_f32_16x16x32_bf16 v[116:119], v[188:191], v[156:159], v[116:119]
	s_setprio 1
	v_mfma_f32_16x16x32_bf16 v[112:115], v[196:199], v[156:159], v[112:115]
	s_mov_b32 m0, s37
	v_lshl_add_u64 v[204:205], s[28:29], 0, v[128:129]
	v_mfma_f32_16x16x32_bf16 v[100:103], v[188:191], v[164:167], v[100:103]
	v_mfma_f32_16x16x32_bf16 v[96:99], v[196:199], v[164:167], v[96:99]
	v_mfma_f32_16x16x32_bf16 v[84:87], v[188:191], v[172:175], v[84:87]
	v_mfma_f32_16x16x32_bf16 v[80:83], v[196:199], v[172:175], v[80:83]
	v_mfma_f32_16x16x32_bf16 v[68:71], v[188:191], v[180:183], v[68:71]
	v_mfma_f32_16x16x32_bf16 v[64:67], v[196:199], v[180:183], v[64:67]
	v_mfma_f32_16x16x32_bf16 v[116:119], v[192:195], v[160:163], v[116:119]
	v_mfma_f32_16x16x32_bf16 v[112:115], v[200:203], v[160:163], v[112:115]
	v_mfma_f32_16x16x32_bf16 v[100:103], v[192:195], v[168:171], v[100:103]
	v_mfma_f32_16x16x32_bf16 v[96:99], v[200:203], v[168:171], v[96:99]
	v_mfma_f32_16x16x32_bf16 v[84:87], v[192:195], v[176:179], v[84:87]
	v_mfma_f32_16x16x32_bf16 v[80:83], v[200:203], v[176:179], v[80:83]
	v_mfma_f32_16x16x32_bf16 v[68:71], v[192:195], v[184:187], v[68:71]
	s_setprio 0
	v_mfma_f32_16x16x32_bf16 v[64:67], v[200:203], v[184:187], v[64:67]
	s_barrier
	ds_read_b128 v[156:159], v135 offset:16384
	ds_read_b128 v[160:163], v135 offset:17408
	ds_read_b128 v[164:167], v135 offset:18432
	ds_read_b128 v[168:171], v135 offset:19456
	ds_read_b128 v[172:175], v135 offset:20480
	ds_read_b128 v[176:179], v135 offset:21504
	ds_read_b128 v[180:183], v135 offset:22528
	ds_read_b128 v[184:187], v135 offset:23552
	global_load_lds_dwordx4 v[204:205], off
	s_mov_b32 m0, s38
	v_lshl_add_u64 v[204:205], s[28:29], 0, v[130:131]
	global_load_lds_dwordx4 v[204:205], off
	s_barrier
	s_waitcnt lgkmcnt(0)
	v_mfma_f32_16x16x32_bf16 v[60:63], v[136:139], v[156:159], v[60:63]
	s_setprio 1
	v_mfma_f32_16x16x32_bf16 v[56:59], v[144:147], v[156:159], v[56:59]
	v_mfma_f32_16x16x32_bf16 v[44:47], v[136:139], v[164:167], v[44:47]
	v_mfma_f32_16x16x32_bf16 v[40:43], v[144:147], v[164:167], v[40:43]
	v_mfma_f32_16x16x32_bf16 v[28:31], v[136:139], v[172:175], v[28:31]
	v_mfma_f32_16x16x32_bf16 v[24:27], v[144:147], v[172:175], v[24:27]
	v_mfma_f32_16x16x32_bf16 v[12:15], v[136:139], v[180:183], v[12:15]
	v_mfma_f32_16x16x32_bf16 v[8:11], v[144:147], v[180:183], v[8:11]
	v_mfma_f32_16x16x32_bf16 v[60:63], v[140:143], v[160:163], v[60:63]
	v_mfma_f32_16x16x32_bf16 v[56:59], v[148:151], v[160:163], v[56:59]
	v_mfma_f32_16x16x32_bf16 v[44:47], v[140:143], v[168:171], v[44:47]
	v_mfma_f32_16x16x32_bf16 v[40:43], v[148:151], v[168:171], v[40:43]
	v_mfma_f32_16x16x32_bf16 v[28:31], v[140:143], v[176:179], v[28:31]
	v_mfma_f32_16x16x32_bf16 v[24:27], v[148:151], v[176:179], v[24:27]
	v_mfma_f32_16x16x32_bf16 v[12:15], v[140:143], v[184:187], v[12:15]
	s_setprio 0
	v_mfma_f32_16x16x32_bf16 v[8:11], v[148:151], v[184:187], v[8:11]
	s_barrier
	s_add_u32 s56, s24, 0x80000
	s_addc_u32 s57, s25, 0
	s_add_i32 s55, s58, s36
	s_mov_b32 m0, s55
	v_lshl_add_u64 v[136:137], s[56:57], 0, v[128:129]
	global_load_lds_dwordx4 v[136:137], off
	s_add_i32 m0, s55, 0x2000
	v_lshl_add_u64 v[136:137], s[56:57], 0, v[130:131]
	global_load_lds_dwordx4 v[136:137], off
	s_waitcnt vmcnt(6)
	s_barrier
	v_mfma_f32_16x16x32_bf16 v[52:55], v[188:191], v[156:159], v[52:55]
	s_setprio 1
	v_mfma_f32_16x16x32_bf16 v[48:51], v[196:199], v[156:159], v[48:51]
	s_add_i32 s55, 0, 0x18000
	v_add_u32_e32 v148, s55, v134
	v_mfma_f32_16x16x32_bf16 v[36:39], v[188:191], v[164:167], v[36:39]
	v_mfma_f32_16x16x32_bf16 v[32:35], v[196:199], v[164:167], v[32:35]
	v_mfma_f32_16x16x32_bf16 v[20:23], v[188:191], v[172:175], v[20:23]
	v_mfma_f32_16x16x32_bf16 v[16:19], v[196:199], v[172:175], v[16:19]
	v_mfma_f32_16x16x32_bf16 v[4:7], v[188:191], v[180:183], v[4:7]
	v_mfma_f32_16x16x32_bf16 v[0:3], v[196:199], v[180:183], v[0:3]
	v_mfma_f32_16x16x32_bf16 v[52:55], v[192:195], v[160:163], v[52:55]
	v_mfma_f32_16x16x32_bf16 v[48:51], v[200:203], v[160:163], v[48:51]
	v_mfma_f32_16x16x32_bf16 v[36:39], v[192:195], v[168:171], v[36:39]
	v_mfma_f32_16x16x32_bf16 v[32:35], v[200:203], v[168:171], v[32:35]
	v_mfma_f32_16x16x32_bf16 v[20:23], v[192:195], v[176:179], v[20:23]
	v_mfma_f32_16x16x32_bf16 v[16:19], v[200:203], v[176:179], v[16:19]
	v_mfma_f32_16x16x32_bf16 v[4:7], v[192:195], v[184:187], v[4:7]
	s_setprio 0
	v_mfma_f32_16x16x32_bf16 v[0:3], v[200:203], v[184:187], v[0:3]
	s_barrier
	ds_read_b128 v[136:139], v148
	ds_read_b128 v[140:143], v148 offset:1024
	ds_read_b128 v[144:147], v148 offset:2048
	ds_read_b128 v[148:151], v148 offset:3072
	s_add_u32 s28, s28, 0x80000
	s_addc_u32 s29, s29, 0
	ds_read_b128 v[156:159], v135 offset:32768
	ds_read_b128 v[160:163], v135 offset:33792
	ds_read_b128 v[164:167], v135 offset:34816
	ds_read_b128 v[168:171], v135 offset:35840
	ds_read_b128 v[172:175], v135 offset:36864
	ds_read_b128 v[176:179], v135 offset:37888
	ds_read_b128 v[180:183], v135 offset:38912
	ds_read_b128 v[184:187], v135 offset:39936
	s_waitcnt lgkmcnt(8)
	s_barrier
; #define PG8_STAGE(bufoff, gbase, voff) do { _Pragma("unroll") for (int _i = 0; _i < 2; ++_i) \
;         __builtin_amdgcn_global_load_lds((const unsigned*)((const char*)(gbase) + (voff)[_i]), (LAS unsigned*)(lds + (bufoff) + ldsw + _i * 8192), 16, 0, 0); } while (0)
; #define PG8_LDA(dst, b, h) do { _Pragma("unroll") for (int m = 0; m < 4; ++m) _Pragma("unroll") for (int k = 0; k < 2; ++k) dst[m][k] = *(const LAS bf16x8*)(lds + PG8_SA(b, h) + aoff + m * 2048 + k * 1024); } while (0)
; #define PG8_LDB(dst, b, h) do { _Pragma("unroll") for (int n = 0; n < 2; ++n) _Pragma("unroll") for (int k = 0; k < 2; ++k) dst[n][k] = *(const LAS bf16x8*)(lds + PG8_SB(b, h) + boff + n * 2048 + k * 1024); } while (0)
; #define PG8_MMA(ai, bj, At, Bt) do { __builtin_amdgcn_s_setprio(1); _Pragma("unroll") for (int m = 0; m < 4; ++m) _Pragma("unroll") for (int n = 0; n < 2; ++n) _Pragma("unroll") for (int k = 0; k < 2; ++k) \
;         acc[ai][bj][m][n] = __builtin_amdgcn_mfma_f32_16x16x32_bf16(Bt[n][k], At[m][k], acc[ai][bj][m][n], 0, 0, 0); __builtin_amdgcn_s_setprio(0); } while (0)
; #define PG8_WAIT_V(n) asm volatile("s_waitcnt vmcnt(" #n ")" ::: "memory")
; #define PG8_WAIT_L(n) asm volatile("s_waitcnt lgkmcnt(" #n ")" ::: "memory")
; #define PG8_BAR __builtin_amdgcn_s_barrier()
; #define PG8_SCHED __builtin_amdgcn_sched_barrier(0)
; template <class Epi>
; __device__ __forceinline__ void gemm_phase(LAS unsigned char* lds, const Gemm g, const StaticOrder& S, const Epi& E) {
;     ...
;             PG8_WAIT_L(8); PG8_BAR; PG8_WAIT_L(0); PG8_MMA(0, 0, At, B0); PG8_BAR; PG8_SCHED;
;             PG8_LDB(B1, 1, 1); PG8_STAGE(PG8_SB(1, 0), b3, voffB);
;             PG8_BAR; PG8_WAIT_L(0); PG8_MMA(0, 1, At, B1); PG8_BAR;
;             PG8_LDA(At, 1, 1); PG8_STAGE(PG8_SA(1, 0), a3, voffA);
;             PG8_BAR; PG8_WAIT_L(0); PG8_MMA(1, 0, At, B0); PG8_BAR; PG8_SCHED;
;             PG8_STAGE(PG8_SB(1, 1), b3 + hstepB, voffB);
;             PG8_WAIT_V(6); PG8_BAR; PG8_MMA(1, 1, At, B1); PG8_BAR;
;         }
	s_waitcnt lgkmcnt(0)
	v_mfma_f32_16x16x32_bf16 v[124:127], v[136:139], v[156:159], v[124:127]
	s_setprio 1
	v_mfma_f32_16x16x32_bf16 v[120:123], v[144:147], v[156:159], v[120:123]
	v_mfma_f32_16x16x32_bf16 v[108:111], v[136:139], v[164:167], v[108:111]
	s_mov_b32 m0, s39
	v_lshl_add_u64 v[188:189], s[28:29], 0, v[128:129]
	global_load_lds_dwordx4 v[188:189], off
	v_mfma_f32_16x16x32_bf16 v[104:107], v[144:147], v[164:167], v[104:107]
	v_mfma_f32_16x16x32_bf16 v[92:95], v[136:139], v[172:175], v[92:95]
	v_mfma_f32_16x16x32_bf16 v[88:91], v[144:147], v[172:175], v[88:91]
	v_mfma_f32_16x16x32_bf16 v[76:79], v[136:139], v[180:183], v[76:79]
	s_mov_b32 m0, s40
	v_lshl_add_u64 v[188:189], s[28:29], 0, v[130:131]
	global_load_lds_dwordx4 v[188:189], off
	v_mfma_f32_16x16x32_bf16 v[72:75], v[144:147], v[180:183], v[72:75]
	v_mfma_f32_16x16x32_bf16 v[124:127], v[140:143], v[160:163], v[124:127]
	v_mfma_f32_16x16x32_bf16 v[120:123], v[148:151], v[160:163], v[120:123]
	v_mfma_f32_16x16x32_bf16 v[108:111], v[140:143], v[168:171], v[108:111]
	v_mfma_f32_16x16x32_bf16 v[104:107], v[148:151], v[168:171], v[104:107]
	v_mfma_f32_16x16x32_bf16 v[92:95], v[140:143], v[176:179], v[92:95]
	v_mfma_f32_16x16x32_bf16 v[88:91], v[148:151], v[176:179], v[88:91]
	v_mfma_f32_16x16x32_bf16 v[76:79], v[140:143], v[184:187], v[76:79]
	s_setprio 0
	v_mfma_f32_16x16x32_bf16 v[72:75], v[148:151], v[184:187], v[72:75]
	s_barrier
	s_add_i32 s56, 0, 0x1c000
	s_add_u32 s28, s24, 0x4000
	s_addc_u32 s29, s25, 0
	s_add_i32 s55, s55, s36
	v_add_u32_e32 v152, s56, v134
	v_lshl_add_u64 v[204:205], s[28:29], 0, v[128:129]
	s_mov_b32 m0, s55
	ds_read_b128 v[188:191], v152
	ds_read_b128 v[192:195], v152 offset:1024
	ds_read_b128 v[196:199], v152 offset:2048
	ds_read_b128 v[200:203], v152 offset:3072
	global_load_lds_dwordx4 v[204:205], off
	s_add_i32 m0, s55, 0x2000
	v_lshl_add_u64 v[204:205], s[28:29], 0, v[130:131]
	global_load_lds_dwordx4 v[204:205], off
	s_barrier
	s_waitcnt lgkmcnt(0)
	v_mfma_f32_16x16x32_bf16 v[116:119], v[188:191], v[156:159], v[116:119]
	s_setprio 1
	v_mfma_f32_16x16x32_bf16 v[112:115], v[196:199], v[156:159], v[112:115]
	s_mov_b32 m0, s43
	v_lshl_add_u64 v[204:205], s[26:27], 0, v[128:129]
	v_mfma_f32_16x16x32_bf16 v[100:103], v[188:191], v[164:167], v[100:103]
	v_mfma_f32_16x16x32_bf16 v[96:99], v[196:199], v[164:167], v[96:99]
	v_mfma_f32_16x16x32_bf16 v[84:87], v[188:191], v[172:175], v[84:87]
	v_mfma_f32_16x16x32_bf16 v[80:83], v[196:199], v[172:175], v[80:83]
	v_mfma_f32_16x16x32_bf16 v[68:71], v[188:191], v[180:183], v[68:71]
	v_mfma_f32_16x16x32_bf16 v[64:67], v[196:199], v[180:183], v[64:67]
	v_mfma_f32_16x16x32_bf16 v[116:119], v[192:195], v[160:163], v[116:119]
	v_mfma_f32_16x16x32_bf16 v[112:115], v[200:203], v[160:163], v[112:115]
	v_mfma_f32_16x16x32_bf16 v[100:103], v[192:195], v[168:171], v[100:103]
	v_mfma_f32_16x16x32_bf16 v[96:99], v[200:203], v[168:171], v[96:99]
	v_mfma_f32_16x16x32_bf16 v[84:87], v[192:195], v[176:179], v[84:87]
	v_mfma_f32_16x16x32_bf16 v[80:83], v[200:203], v[176:179], v[80:83]
	v_mfma_f32_16x16x32_bf16 v[68:71], v[192:195], v[184:187], v[68:71]
	s_setprio 0
	v_mfma_f32_16x16x32_bf16 v[64:67], v[200:203], v[184:187], v[64:67]
	s_barrier
	ds_read_b128 v[156:159], v135 offset:49152
	ds_read_b128 v[160:163], v135 offset:50176
	ds_read_b128 v[164:167], v135 offset:51200
	ds_read_b128 v[168:171], v135 offset:52224
	ds_read_b128 v[172:175], v135 offset:53248
	ds_read_b128 v[176:179], v135 offset:54272
	ds_read_b128 v[180:183], v135 offset:55296
	ds_read_b128 v[184:187], v135 offset:56320
	global_load_lds_dwordx4 v[204:205], off
	s_mov_b32 m0, s44
	v_lshl_add_u64 v[204:205], s[26:27], 0, v[130:131]
	global_load_lds_dwordx4 v[204:205], off
	s_barrier
	s_waitcnt lgkmcnt(0)
	v_mfma_f32_16x16x32_bf16 v[60:63], v[136:139], v[156:159], v[60:63]
	s_setprio 1
	v_mfma_f32_16x16x32_bf16 v[56:59], v[144:147], v[156:159], v[56:59]
	v_mfma_f32_16x16x32_bf16 v[44:47], v[136:139], v[164:167], v[44:47]
	v_mfma_f32_16x16x32_bf16 v[40:43], v[144:147], v[164:167], v[40:43]
	v_mfma_f32_16x16x32_bf16 v[28:31], v[136:139], v[172:175], v[28:31]
	v_mfma_f32_16x16x32_bf16 v[24:27], v[144:147], v[172:175], v[24:27]
	v_mfma_f32_16x16x32_bf16 v[12:15], v[136:139], v[180:183], v[12:15]
	v_mfma_f32_16x16x32_bf16 v[8:11], v[144:147], v[180:183], v[8:11]
	v_mfma_f32_16x16x32_bf16 v[60:63], v[140:143], v[160:163], v[60:63]
	v_mfma_f32_16x16x32_bf16 v[56:59], v[148:151], v[160:163], v[56:59]
	v_mfma_f32_16x16x32_bf16 v[44:47], v[140:143], v[168:171], v[44:47]
	v_mfma_f32_16x16x32_bf16 v[40:43], v[148:151], v[168:171], v[40:43]
	v_mfma_f32_16x16x32_bf16 v[28:31], v[140:143], v[176:179], v[28:31]
	v_mfma_f32_16x16x32_bf16 v[24:27], v[148:151], v[176:179], v[24:27]
	v_mfma_f32_16x16x32_bf16 v[12:15], v[140:143], v[184:187], v[12:15]
	s_setprio 0
	v_mfma_f32_16x16x32_bf16 v[8:11], v[148:151], v[184:187], v[8:11]
	s_barrier
	s_add_u32 s24, s24, 0x84000
	s_addc_u32 s25, s25, 0
	s_add_i32 s26, s56, s36
	s_mov_b32 m0, s26
	v_lshl_add_u64 v[136:137], s[24:25], 0, v[128:129]
	global_load_lds_dwordx4 v[136:137], off
	s_add_i32 m0, s26, 0x2000
	v_lshl_add_u64 v[136:137], s[24:25], 0, v[130:131]
	global_load_lds_dwordx4 v[136:137], off
	s_waitcnt vmcnt(6)
	s_barrier
	v_mfma_f32_16x16x32_bf16 v[52:55], v[188:191], v[156:159], v[52:55]
	s_setprio 1
	v_mfma_f32_16x16x32_bf16 v[48:51], v[196:199], v[156:159], v[48:51]
	s_add_i32 s54, s54, 2
	s_add_u32 s22, s22, 0x8000
	s_addc_u32 s23, s23, 0
	s_add_u32 s51, s51, 0x8000
	s_addc_u32 s52, s52, 0
	v_mfma_f32_16x16x32_bf16 v[36:39], v[188:191], v[164:167], v[36:39]
	v_mfma_f32_16x16x32_bf16 v[32:35], v[196:199], v[164:167], v[32:35]
	v_mfma_f32_16x16x32_bf16 v[20:23], v[188:191], v[172:175], v[20:23]
	v_mfma_f32_16x16x32_bf16 v[16:19], v[196:199], v[172:175], v[16:19]
	v_mfma_f32_16x16x32_bf16 v[4:7], v[188:191], v[180:183], v[4:7]
	v_mfma_f32_16x16x32_bf16 v[0:3], v[196:199], v[180:183], v[0:3]
	v_mfma_f32_16x16x32_bf16 v[52:55], v[192:195], v[160:163], v[52:55]
	v_mfma_f32_16x16x32_bf16 v[48:51], v[200:203], v[160:163], v[48:51]
	v_mfma_f32_16x16x32_bf16 v[36:39], v[192:195], v[168:171], v[36:39]
	v_mfma_f32_16x16x32_bf16 v[32:35], v[200:203], v[168:171], v[32:35]
	v_mfma_f32_16x16x32_bf16 v[20:23], v[192:195], v[176:179], v[20:23]
	v_mfma_f32_16x16x32_bf16 v[16:19], v[200:203], v[176:179], v[16:19]
	v_mfma_f32_16x16x32_bf16 v[4:7], v[192:195], v[184:187], v[4:7]
	s_cmp_gt_u32 s54, 29
	s_setprio 0
	v_mfma_f32_16x16x32_bf16 v[0:3], v[200:203], v[184:187], v[0:3]
	s_barrier
	s_cbranch_scc0 .LBB0_141

; #define PG8_STAGE(bufoff, gbase, voff) do { _Pragma("unroll") for (int _i = 0; _i < 2; ++_i) \
;         __builtin_amdgcn_global_load_lds((const unsigned*)((const char*)(gbase) + (voff)[_i]), (LAS unsigned*)(lds + (bufoff) + ldsw + _i * 8192), 16, 0, 0); } while (0)
; #define PG8_LDA(dst, b, h) do { _Pragma("unroll") for (int m = 0; m < 4; ++m) _Pragma("unroll") for (int k = 0; k < 2; ++k) dst[m][k] = *(const LAS bf16x8*)(lds + PG8_SA(b, h) + aoff + m * 2048 + k * 1024); } while (0)
; #define PG8_LDB(dst, b, h) do { _Pragma("unroll") for (int n = 0; n < 2; ++n) _Pragma("unroll") for (int k = 0; k < 2; ++k) dst[n][k] = *(const LAS bf16x8*)(lds + PG8_SB(b, h) + boff + n * 2048 + k * 1024); } while (0)
; #define PG8_WAIT_V(n) asm volatile("s_waitcnt vmcnt(" #n ")" ::: "memory")
; #define PG8_WAIT_L(n) asm volatile("s_waitcnt lgkmcnt(" #n ")" ::: "memory")
; #define PG8_BAR __builtin_amdgcn_s_barrier()
; #define PG8_SCHED __builtin_amdgcn_sched_barrier(0)
; template <class Epi>
; __device__ __forceinline__ void gemm_phase(LAS unsigned char* lds, const Gemm g, const StaticOrder& S, const Epi& E) {
;     ...
;         for (int t = 0; t < nt; t += 2) {
;             const bool last = (t == nt - 2);
;             const char* a1 = cA + (size_t)(t + 1) * kstep;
;             const char* a2 = last ? nA : cA + (size_t)(t + 2) * kstep; const char* b2 = last ? nB : cB + (size_t)(t + 2) * kstep;
;             const char* a3 = a2 + kstep; const char* b3 = b2 + kstep;
;             PG8_LDB(B0, 0, 0); PG8_SCHED; PG8_LDA(At, 0, 0); PG8_STAGE(PG8_SA(1, 1), a1 + hstepA, voffA);
;             PG8_WAIT_L(8); PG8_BAR; PG8_WAIT_L(0); PG8_MMA(0, 0, At, B0); PG8_BAR; PG8_SCHED;
;             PG8_LDB(B1, 0, 1); PG8_STAGE(PG8_SB(0, 0), b2, voffB);
;             PG8_BAR; PG8_WAIT_L(0); PG8_MMA(0, 1, At, B1); PG8_BAR;
;             PG8_LDA(At, 0, 1); PG8_STAGE(PG8_SA(0, 0), a2, voffA);
;             PG8_BAR; PG8_WAIT_L(0); PG8_MMA(1, 0, At, B0); PG8_BAR; PG8_SCHED;
;             PG8_STAGE(PG8_SB(0, 1), b2 + hstepB, voffB);
;             PG8_WAIT_V(6); PG8_BAR; PG8_MMA(1, 1, At, B1); PG8_BAR;
;             PG8_LDB(B0, 1, 0); PG8_SCHED; PG8_LDA(At, 1, 0); PG8_STAGE(PG8_SA(0, 1), a2 + hstepA, voffA);
;             PG8_WAIT_L(8); PG8_BAR; PG8_WAIT_L(0); PG8_MMA(0, 0, At, B0); PG8_BAR; PG8_SCHED;
.LBB0_186:
	s_add_u32 s4, s24, 0x4000
	s_addc_u32 s5, s25, 0
	s_add_u32 s50, s22, 0x8000
	s_addc_u32 s51, s23, 0
	s_mov_b32 s22, 0
	s_add_i32 s54, s22, 2
	s_add_u32 s23, s4, 0x4000
	s_addc_u32 s24, s5, 0
	s_cmp_eq_u32 s40, s22
	s_cselect_b32 s26, s6, s23
	s_cselect_b32 s27, s7, s24
	s_cselect_b32 s24, s20, s50
	s_cselect_b32 s25, s21, s51
	s_add_u32 s22, s26, 0x4000
	s_addc_u32 s23, s27, 0
	s_add_i32 s55, 0, 0x10000
	v_add_u32_e32 v140, s55, v207
	ds_read_b128 v[128:131], v140
	ds_read_b128 v[132:135], v140 offset:1024
	ds_read_b128 v[136:139], v140 offset:2048
	ds_read_b128 v[140:143], v140 offset:3072
	ds_read_b128 v[144:147], v209
	ds_read_b128 v[148:151], v209 offset:1024
	ds_read_b128 v[162:165], v209 offset:2048
	ds_read_b128 v[166:169], v209 offset:3072
	ds_read_b128 v[170:173], v209 offset:4096
	ds_read_b128 v[174:177], v209 offset:5120
	ds_read_b128 v[178:181], v209 offset:6144
	ds_read_b128 v[182:185], v209 offset:7168
	s_waitcnt lgkmcnt(8)
	s_barrier
	s_waitcnt lgkmcnt(0)
	v_mfma_f32_16x16x32_bf16 v[124:127], v[128:131], v[144:147], 0
	s_setprio 1
	v_mfma_f32_16x16x32_bf16 v[120:123], v[136:139], v[144:147], 0
	v_mfma_f32_16x16x32_bf16 v[116:119], v[128:131], v[162:165], 0
	s_add_i32 m0, s33, 0xc000
	v_lshl_add_u64 v[186:187], s[4:5], 0, v[158:159]
	global_load_lds_dwordx4 v[186:187], off
	v_mfma_f32_16x16x32_bf16 v[112:115], v[136:139], v[162:165], 0
	v_mfma_f32_16x16x32_bf16 v[108:111], v[128:131], v[170:173], 0
	v_mfma_f32_16x16x32_bf16 v[104:107], v[136:139], v[170:173], 0
	v_mfma_f32_16x16x32_bf16 v[100:103], v[128:131], v[178:181], 0
	s_add_i32 m0, s33, 0xe000
	v_lshl_add_u64 v[186:187], s[4:5], 0, v[160:161]
	global_load_lds_dwordx4 v[186:187], off
	v_mfma_f32_16x16x32_bf16 v[96:99], v[136:139], v[178:181], 0
	v_mfma_f32_16x16x32_bf16 v[124:127], v[132:135], v[148:151], v[124:127]
	v_mfma_f32_16x16x32_bf16 v[120:123], v[140:143], v[148:151], v[120:123]
	v_mfma_f32_16x16x32_bf16 v[116:119], v[132:135], v[166:169], v[116:119]
	v_mfma_f32_16x16x32_bf16 v[112:115], v[140:143], v[166:169], v[112:115]
	v_mfma_f32_16x16x32_bf16 v[108:111], v[132:135], v[174:177], v[108:111]
	v_mfma_f32_16x16x32_bf16 v[104:107], v[140:143], v[174:177], v[104:107]
	v_mfma_f32_16x16x32_bf16 v[100:103], v[132:135], v[182:185], v[100:103]
	s_setprio 0
	v_mfma_f32_16x16x32_bf16 v[96:99], v[140:143], v[182:185], v[96:99]
	s_barrier
	s_add_i32 s58, 0, 0x14000
	s_add_i32 s55, s55, s31
	v_add_u32_e32 v198, s58, v207
	v_lshl_add_u64 v[202:203], s[24:25], 0, v[152:153]
	s_mov_b32 m0, s55
	ds_read_b128 v[186:189], v198
	ds_read_b128 v[190:193], v198 offset:1024
	ds_read_b128 v[194:197], v198 offset:2048
	ds_read_b128 v[198:201], v198 offset:3072
	global_load_lds_dwordx4 v[202:203], off
	s_add_i32 m0, s55, 0x2000
	v_lshl_add_u64 v[202:203], s[24:25], 0, v[156:157]
	global_load_lds_dwordx4 v[202:203], off
	s_barrier
	s_waitcnt lgkmcnt(0)
	v_mfma_f32_16x16x32_bf16 v[92:95], v[186:189], v[144:147], 0
	s_setprio 1
	v_mfma_f32_16x16x32_bf16 v[88:91], v[194:197], v[144:147], 0
	s_mov_b32 m0, s33
	v_lshl_add_u64 v[202:203], s[26:27], 0, v[152:153]
	v_mfma_f32_16x16x32_bf16 v[84:87], v[186:189], v[162:165], 0
	v_mfma_f32_16x16x32_bf16 v[80:83], v[194:197], v[162:165], 0
	v_mfma_f32_16x16x32_bf16 v[76:79], v[186:189], v[170:173], 0
	v_mfma_f32_16x16x32_bf16 v[72:75], v[194:197], v[170:173], 0
	v_mfma_f32_16x16x32_bf16 v[68:71], v[186:189], v[178:181], 0
	v_mfma_f32_16x16x32_bf16 v[64:67], v[194:197], v[178:181], 0
	v_mfma_f32_16x16x32_bf16 v[92:95], v[190:193], v[148:151], v[92:95]
	v_mfma_f32_16x16x32_bf16 v[88:91], v[198:201], v[148:151], v[88:91]
	v_mfma_f32_16x16x32_bf16 v[84:87], v[190:193], v[166:169], v[84:87]
	v_mfma_f32_16x16x32_bf16 v[80:83], v[198:201], v[166:169], v[80:83]
	v_mfma_f32_16x16x32_bf16 v[76:79], v[190:193], v[174:177], v[76:79]
	v_mfma_f32_16x16x32_bf16 v[72:75], v[198:201], v[174:177], v[72:75]
	v_mfma_f32_16x16x32_bf16 v[68:71], v[190:193], v[182:185], v[68:71]
	s_setprio 0
	v_mfma_f32_16x16x32_bf16 v[64:67], v[198:201], v[182:185], v[64:67]
	s_barrier
	ds_read_b128 v[144:147], v209 offset:16384
	ds_read_b128 v[148:151], v209 offset:17408
	ds_read_b128 v[162:165], v209 offset:18432
	ds_read_b128 v[166:169], v209 offset:19456
	ds_read_b128 v[170:173], v209 offset:20480
	ds_read_b128 v[174:177], v209 offset:21504
	ds_read_b128 v[178:181], v209 offset:22528
	ds_read_b128 v[182:185], v209 offset:23552
	global_load_lds_dwordx4 v[202:203], off
	s_mov_b32 m0, s34
	v_lshl_add_u64 v[202:203], s[26:27], 0, v[156:157]
	global_load_lds_dwordx4 v[202:203], off
	s_barrier
	s_waitcnt lgkmcnt(0)
	v_mfma_f32_16x16x32_bf16 v[60:63], v[128:131], v[144:147], 0
	s_setprio 1
	v_mfma_f32_16x16x32_bf16 v[56:59], v[136:139], v[144:147], 0
	v_mfma_f32_16x16x32_bf16 v[52:55], v[128:131], v[162:165], 0
	v_mfma_f32_16x16x32_bf16 v[48:51], v[136:139], v[162:165], 0
	v_mfma_f32_16x16x32_bf16 v[44:47], v[128:131], v[170:173], 0
	v_mfma_f32_16x16x32_bf16 v[40:43], v[136:139], v[170:173], 0
	v_mfma_f32_16x16x32_bf16 v[36:39], v[128:131], v[178:181], 0
	v_mfma_f32_16x16x32_bf16 v[32:35], v[136:139], v[178:181], 0
	v_mfma_f32_16x16x32_bf16 v[60:63], v[132:135], v[148:151], v[60:63]
	v_mfma_f32_16x16x32_bf16 v[56:59], v[140:143], v[148:151], v[56:59]
	v_mfma_f32_16x16x32_bf16 v[52:55], v[132:135], v[166:169], v[52:55]
	v_mfma_f32_16x16x32_bf16 v[48:51], v[140:143], v[166:169], v[48:51]
	v_mfma_f32_16x16x32_bf16 v[44:47], v[132:135], v[174:177], v[44:47]
	v_mfma_f32_16x16x32_bf16 v[40:43], v[140:143], v[174:177], v[40:43]
	v_mfma_f32_16x16x32_bf16 v[36:39], v[132:135], v[182:185], v[36:39]
	s_setprio 0
	v_mfma_f32_16x16x32_bf16 v[32:35], v[140:143], v[182:185], v[32:35]
	s_barrier
; #define PG8_STAGE(bufoff, gbase, voff) do { _Pragma("unroll") for (int _i = 0; _i < 2; ++_i) \
;         __builtin_amdgcn_global_load_lds((const unsigned*)((const char*)(gbase) + (voff)[_i]), (LAS unsigned*)(lds + (bufoff) + ldsw + _i * 8192), 16, 0, 0); } while (0)
; #define PG8_LDA(dst, b, h) do { _Pragma("unroll") for (int m = 0; m < 4; ++m) _Pragma("unroll") for (int k = 0; k < 2; ++k) dst[m][k] = *(const LAS bf16x8*)(lds + PG8_SA(b, h) + aoff + m * 2048 + k * 1024); } while (0)
; #define PG8_LDB(dst, b, h) do { _Pragma("unroll") for (int n = 0; n < 2; ++n) _Pragma("unroll") for (int k = 0; k < 2; ++k) dst[n][k] = *(const LAS bf16x8*)(lds + PG8_SB(b, h) + boff + n * 2048 + k * 1024); } while (0)
; #define PG8_MMA(ai, bj, At, Bt) do { __builtin_amdgcn_s_setprio(1); _Pragma("unroll") for (int m = 0; m < 4; ++m) _Pragma("unroll") for (int n = 0; n < 2; ++n) _Pragma("unroll") for (int k = 0; k < 2; ++k) \
;         acc[ai][bj][m][n] = __builtin_amdgcn_mfma_f32_16x16x32_bf16(Bt[n][k], At[m][k], acc[ai][bj][m][n], 0, 0, 0); __builtin_amdgcn_s_setprio(0); } while (0)
; #define PG8_WAIT_V(n) asm volatile("s_waitcnt vmcnt(" #n ")" ::: "memory")
; #define PG8_WAIT_L(n) asm volatile("s_waitcnt lgkmcnt(" #n ")" ::: "memory")
; #define PG8_BAR __builtin_amdgcn_s_barrier()
; #define PG8_SCHED __builtin_amdgcn_sched_barrier(0)
; template <class Epi>
; __device__ __forceinline__ void gemm_phase(LAS unsigned char* lds, const Gemm g, const StaticOrder& S, const Epi& E) {
;     ...
;             PG8_STAGE(PG8_SB(0, 1), b2 + hstepB, voffB);
;             PG8_WAIT_V(6); PG8_BAR; PG8_MMA(1, 1, At, B1); PG8_BAR;
;             PG8_LDB(B0, 1, 0); PG8_SCHED; PG8_LDA(At, 1, 0); PG8_STAGE(PG8_SA(0, 1), a2 + hstepA, voffA);
;             PG8_WAIT_L(8); PG8_BAR; PG8_WAIT_L(0); PG8_MMA(0, 0, At, B0); PG8_BAR; PG8_SCHED;
;             PG8_LDB(B1, 1, 1); PG8_STAGE(PG8_SB(1, 0), b3, voffB);
;             PG8_BAR; PG8_WAIT_L(0); PG8_MMA(0, 1, At, B1); PG8_BAR;
;             PG8_LDA(At, 1, 1); PG8_STAGE(PG8_SA(1, 0), a3, voffA);
;             PG8_BAR; PG8_WAIT_L(0); PG8_MMA(1, 0, At, B0); PG8_BAR; PG8_SCHED;
	s_add_u32 s56, s24, s52
	s_addc_u32 s57, s25, 0
	s_add_i32 s55, s58, s31
	s_mov_b32 m0, s55
	v_lshl_add_u64 v[128:129], s[56:57], 0, v[152:153]
	global_load_lds_dwordx4 v[128:129], off
	s_add_i32 m0, s55, 0x2000
	v_lshl_add_u64 v[128:129], s[56:57], 0, v[156:157]
	global_load_lds_dwordx4 v[128:129], off
	s_waitcnt vmcnt(6)
	s_barrier
	v_mfma_f32_16x16x32_bf16 v[28:31], v[186:189], v[144:147], 0
	s_setprio 1
	v_mfma_f32_16x16x32_bf16 v[24:27], v[194:197], v[144:147], 0
	s_add_i32 s55, 0, 0x18000
	v_add_u32_e32 v140, s55, v207
	v_mfma_f32_16x16x32_bf16 v[20:23], v[186:189], v[162:165], 0
	v_mfma_f32_16x16x32_bf16 v[16:19], v[194:197], v[162:165], 0
	v_mfma_f32_16x16x32_bf16 v[12:15], v[186:189], v[170:173], 0
	v_mfma_f32_16x16x32_bf16 v[8:11], v[194:197], v[170:173], 0
	v_mfma_f32_16x16x32_bf16 v[4:7], v[186:189], v[178:181], 0
	v_mfma_f32_16x16x32_bf16 v[0:3], v[194:197], v[178:181], 0
	v_mfma_f32_16x16x32_bf16 v[28:31], v[190:193], v[148:151], v[28:31]
	v_mfma_f32_16x16x32_bf16 v[24:27], v[198:201], v[148:151], v[24:27]
	v_mfma_f32_16x16x32_bf16 v[20:23], v[190:193], v[166:169], v[20:23]
	v_mfma_f32_16x16x32_bf16 v[16:19], v[198:201], v[166:169], v[16:19]
	v_mfma_f32_16x16x32_bf16 v[12:15], v[190:193], v[174:177], v[12:15]
	v_mfma_f32_16x16x32_bf16 v[8:11], v[198:201], v[174:177], v[8:11]
	v_mfma_f32_16x16x32_bf16 v[4:7], v[190:193], v[182:185], v[4:7]
	s_setprio 0
	v_mfma_f32_16x16x32_bf16 v[0:3], v[198:201], v[182:185], v[0:3]
	s_barrier
	ds_read_b128 v[128:131], v140
	ds_read_b128 v[132:135], v140 offset:1024
	ds_read_b128 v[136:139], v140 offset:2048
	ds_read_b128 v[140:143], v140 offset:3072
	s_add_u32 s26, s26, s52
	s_addc_u32 s27, s27, 0
	ds_read_b128 v[144:147], v209 offset:32768
	ds_read_b128 v[148:151], v209 offset:33792
	ds_read_b128 v[162:165], v209 offset:34816
	ds_read_b128 v[166:169], v209 offset:35840
	ds_read_b128 v[170:173], v209 offset:36864
	ds_read_b128 v[174:177], v209 offset:37888
	ds_read_b128 v[178:181], v209 offset:38912
	ds_read_b128 v[182:185], v209 offset:39936
	s_waitcnt lgkmcnt(8)
	s_barrier
	s_waitcnt lgkmcnt(0)
	v_mfma_f32_16x16x32_bf16 v[124:127], v[128:131], v[144:147], v[124:127]
	s_setprio 1
	v_mfma_f32_16x16x32_bf16 v[120:123], v[136:139], v[144:147], v[120:123]
	v_mfma_f32_16x16x32_bf16 v[116:119], v[128:131], v[162:165], v[116:119]
	s_mov_b32 m0, s35
	v_lshl_add_u64 v[186:187], s[26:27], 0, v[152:153]
	global_load_lds_dwordx4 v[186:187], off
	v_mfma_f32_16x16x32_bf16 v[112:115], v[136:139], v[162:165], v[112:115]
	v_mfma_f32_16x16x32_bf16 v[108:111], v[128:131], v[170:173], v[108:111]
	v_mfma_f32_16x16x32_bf16 v[104:107], v[136:139], v[170:173], v[104:107]
	v_mfma_f32_16x16x32_bf16 v[100:103], v[128:131], v[178:181], v[100:103]
	s_mov_b32 m0, s36
	v_lshl_add_u64 v[186:187], s[26:27], 0, v[156:157]
	global_load_lds_dwordx4 v[186:187], off
	v_mfma_f32_16x16x32_bf16 v[96:99], v[136:139], v[178:181], v[96:99]
	v_mfma_f32_16x16x32_bf16 v[124:127], v[132:135], v[148:151], v[124:127]
	v_mfma_f32_16x16x32_bf16 v[120:123], v[140:143], v[148:151], v[120:123]
	v_mfma_f32_16x16x32_bf16 v[116:119], v[132:135], v[166:169], v[116:119]
	v_mfma_f32_16x16x32_bf16 v[112:115], v[140:143], v[166:169], v[112:115]
	v_mfma_f32_16x16x32_bf16 v[108:111], v[132:135], v[174:177], v[108:111]
	v_mfma_f32_16x16x32_bf16 v[104:107], v[140:143], v[174:177], v[104:107]
	v_mfma_f32_16x16x32_bf16 v[100:103], v[132:135], v[182:185], v[100:103]
	s_setprio 0
	v_mfma_f32_16x16x32_bf16 v[96:99], v[140:143], v[182:185], v[96:99]
	s_barrier
	s_add_i32 s26, 0, 0x1c000
	s_add_u32 s24, s24, 0x4000
	s_addc_u32 s25, s25, 0
	s_add_i32 s27, s55, s31
	v_add_u32_e32 v198, s26, v207
	v_lshl_add_u64 v[202:203], s[24:25], 0, v[152:153]
	s_mov_b32 m0, s27
	ds_read_b128 v[186:189], v198
	ds_read_b128 v[190:193], v198 offset:1024
	ds_read_b128 v[194:197], v198 offset:2048
	ds_read_b128 v[198:201], v198 offset:3072
	global_load_lds_dwordx4 v[202:203], off
	s_add_i32 m0, s27, 0x2000
	v_lshl_add_u64 v[202:203], s[24:25], 0, v[156:157]
	global_load_lds_dwordx4 v[202:203], off
	s_barrier
	s_waitcnt lgkmcnt(0)
	v_mfma_f32_16x16x32_bf16 v[92:95], v[186:189], v[144:147], v[92:95]
	s_setprio 1
	v_mfma_f32_16x16x32_bf16 v[88:91], v[194:197], v[144:147], v[88:91]
	s_mov_b32 m0, s38
	v_lshl_add_u64 v[202:203], s[22:23], 0, v[152:153]
	v_mfma_f32_16x16x32_bf16 v[84:87], v[186:189], v[162:165], v[84:87]
	v_mfma_f32_16x16x32_bf16 v[80:83], v[194:197], v[162:165], v[80:83]
	v_mfma_f32_16x16x32_bf16 v[76:79], v[186:189], v[170:173], v[76:79]
	v_mfma_f32_16x16x32_bf16 v[72:75], v[194:197], v[170:173], v[72:75]
	v_mfma_f32_16x16x32_bf16 v[68:71], v[186:189], v[178:181], v[68:71]
	v_mfma_f32_16x16x32_bf16 v[64:67], v[194:197], v[178:181], v[64:67]
	v_mfma_f32_16x16x32_bf16 v[92:95], v[190:193], v[148:151], v[92:95]
	v_mfma_f32_16x16x32_bf16 v[88:91], v[198:201], v[148:151], v[88:91]
	v_mfma_f32_16x16x32_bf16 v[84:87], v[190:193], v[166:169], v[84:87]
	v_mfma_f32_16x16x32_bf16 v[80:83], v[198:201], v[166:169], v[80:83]
	v_mfma_f32_16x16x32_bf16 v[76:79], v[190:193], v[174:177], v[76:79]
	v_mfma_f32_16x16x32_bf16 v[72:75], v[198:201], v[174:177], v[72:75]
	v_mfma_f32_16x16x32_bf16 v[68:71], v[190:193], v[182:185], v[68:71]
	s_setprio 0
	v_mfma_f32_16x16x32_bf16 v[64:67], v[198:201], v[182:185], v[64:67]
	s_barrier
	ds_read_b128 v[144:147], v209 offset:49152
	ds_read_b128 v[148:151], v209 offset:50176
	ds_read_b128 v[162:165], v209 offset:51200
	ds_read_b128 v[166:169], v209 offset:52224
	ds_read_b128 v[170:173], v209 offset:53248
	ds_read_b128 v[174:177], v209 offset:54272
	ds_read_b128 v[178:181], v209 offset:55296
	ds_read_b128 v[182:185], v209 offset:56320
	global_load_lds_dwordx4 v[202:203], off
	s_mov_b32 m0, s39
	v_lshl_add_u64 v[202:203], s[22:23], 0, v[156:157]
	global_load_lds_dwordx4 v[202:203], off
	s_barrier
; #define PG8_STAGE(bufoff, gbase, voff) do { _Pragma("unroll") for (int _i = 0; _i < 2; ++_i) \
;         __builtin_amdgcn_global_load_lds((const unsigned*)((const char*)(gbase) + (voff)[_i]), (LAS unsigned*)(lds + (bufoff) + ldsw + _i * 8192), 16, 0, 0); } while (0)
; #define PG8_LDA(dst, b, h) do { _Pragma("unroll") for (int m = 0; m < 4; ++m) _Pragma("unroll") for (int k = 0; k < 2; ++k) dst[m][k] = *(const LAS bf16x8*)(lds + PG8_SA(b, h) + aoff + m * 2048 + k * 1024); } while (0)
; #define PG8_LDB(dst, b, h) do { _Pragma("unroll") for (int n = 0; n < 2; ++n) _Pragma("unroll") for (int k = 0; k < 2; ++k) dst[n][k] = *(const LAS bf16x8*)(lds + PG8_SB(b, h) + boff + n * 2048 + k * 1024); } while (0)
; #define PG8_MMA(ai, bj, At, Bt) do { __builtin_amdgcn_s_setprio(1); _Pragma("unroll") for (int m = 0; m < 4; ++m) _Pragma("unroll") for (int n = 0; n < 2; ++n) _Pragma("unroll") for (int k = 0; k < 2; ++k) \
;         acc[ai][bj][m][n] = __builtin_amdgcn_mfma_f32_16x16x32_bf16(Bt[n][k], At[m][k], acc[ai][bj][m][n], 0, 0, 0); __builtin_amdgcn_s_setprio(0); } while (0)
; #define PG8_WAIT_V(n) asm volatile("s_waitcnt vmcnt(" #n ")" ::: "memory")
; #define PG8_WAIT_L(n) asm volatile("s_waitcnt lgkmcnt(" #n ")" ::: "memory")
; template <class Epi>
; __device__ __forceinline__ void gemm_phase(LAS unsigned char* lds, const Gemm g, const StaticOrder& S, const Epi& E) {
;     ...
;             const bool last = (t == nt - 2);
;             const char* a1 = cA + (size_t)(t + 1) * kstep;
;             const char* a2 = last ? nA : cA + (size_t)(t + 2) * kstep; const char* b2 = last ? nB : cB + (size_t)(t + 2) * kstep;
;             const char* a3 = a2 + kstep; const char* b3 = b2 + kstep;
;             PG8_LDB(B0, 0, 0); PG8_SCHED; PG8_LDA(At, 0, 0); PG8_STAGE(PG8_SA(1, 1), a1 + hstepA, voffA);
;             PG8_WAIT_L(8); PG8_BAR; PG8_WAIT_L(0); PG8_MMA(0, 0, At, B0); PG8_BAR; PG8_SCHED;
;             PG8_LDB(B1, 0, 1); PG8_STAGE(PG8_SB(0, 0), b2, voffB);
;             PG8_BAR; PG8_WAIT_L(0); PG8_MMA(0, 1, At, B1); PG8_BAR;
;     ...
;             PG8_BAR; PG8_WAIT_L(0); PG8_MMA(0, 1, At, B1); PG8_BAR;
;             PG8_LDA(At, 1, 1); PG8_STAGE(PG8_SA(1, 0), a3, voffA);
;             PG8_BAR; PG8_WAIT_L(0); PG8_MMA(1, 0, At, B0); PG8_BAR; PG8_SCHED;
;             PG8_STAGE(PG8_SB(1, 1), b3 + hstepB, voffB);
;             PG8_WAIT_V(6); PG8_BAR; PG8_MMA(1, 1, At, B1); PG8_BAR;
;         }
	s_waitcnt lgkmcnt(0)
	v_mfma_f32_16x16x32_bf16 v[60:63], v[128:131], v[144:147], v[60:63]
	s_setprio 1
	v_mfma_f32_16x16x32_bf16 v[56:59], v[136:139], v[144:147], v[56:59]
	v_mfma_f32_16x16x32_bf16 v[52:55], v[128:131], v[162:165], v[52:55]
	v_mfma_f32_16x16x32_bf16 v[48:51], v[136:139], v[162:165], v[48:51]
	v_mfma_f32_16x16x32_bf16 v[44:47], v[128:131], v[170:173], v[44:47]
	v_mfma_f32_16x16x32_bf16 v[40:43], v[136:139], v[170:173], v[40:43]
	v_mfma_f32_16x16x32_bf16 v[36:39], v[128:131], v[178:181], v[36:39]
	v_mfma_f32_16x16x32_bf16 v[32:35], v[136:139], v[178:181], v[32:35]
	v_mfma_f32_16x16x32_bf16 v[60:63], v[132:135], v[148:151], v[60:63]
	v_mfma_f32_16x16x32_bf16 v[56:59], v[140:143], v[148:151], v[56:59]
	v_mfma_f32_16x16x32_bf16 v[52:55], v[132:135], v[166:169], v[52:55]
	v_mfma_f32_16x16x32_bf16 v[48:51], v[140:143], v[166:169], v[48:51]
	v_mfma_f32_16x16x32_bf16 v[44:47], v[132:135], v[174:177], v[44:47]
	v_mfma_f32_16x16x32_bf16 v[40:43], v[140:143], v[174:177], v[40:43]
	v_mfma_f32_16x16x32_bf16 v[36:39], v[132:135], v[182:185], v[36:39]
	s_setprio 0
	v_mfma_f32_16x16x32_bf16 v[32:35], v[140:143], v[182:185], v[32:35]
	s_barrier
	s_add_u32 s22, s24, s52
	s_addc_u32 s23, s25, 0
	s_add_i32 s24, s26, s31
	s_mov_b32 m0, s24
	v_lshl_add_u64 v[128:129], s[22:23], 0, v[152:153]
	global_load_lds_dwordx4 v[128:129], off
	s_add_i32 m0, s24, 0x2000
	v_lshl_add_u64 v[128:129], s[22:23], 0, v[156:157]
	global_load_lds_dwordx4 v[128:129], off
	s_waitcnt vmcnt(6)
	s_barrier
	v_mfma_f32_16x16x32_bf16 v[28:31], v[186:189], v[144:147], v[28:31]
	s_setprio 1
	v_mfma_f32_16x16x32_bf16 v[24:27], v[194:197], v[144:147], v[24:27]
	s_add_u32 s4, s4, 0x8000
	s_addc_u32 s5, s5, 0
	s_add_u32 s50, s50, 0x8000
	s_addc_u32 s51, s51, 0
	v_mfma_f32_16x16x32_bf16 v[20:23], v[186:189], v[162:165], v[20:23]
	v_mfma_f32_16x16x32_bf16 v[16:19], v[194:197], v[162:165], v[16:19]
	v_mfma_f32_16x16x32_bf16 v[12:15], v[186:189], v[170:173], v[12:15]
	v_mfma_f32_16x16x32_bf16 v[8:11], v[194:197], v[170:173], v[8:11]
	v_mfma_f32_16x16x32_bf16 v[4:7], v[186:189], v[178:181], v[4:7]
	v_mfma_f32_16x16x32_bf16 v[0:3], v[194:197], v[178:181], v[0:3]
	v_mfma_f32_16x16x32_bf16 v[28:31], v[190:193], v[148:151], v[28:31]
	v_mfma_f32_16x16x32_bf16 v[24:27], v[198:201], v[148:151], v[24:27]
	v_mfma_f32_16x16x32_bf16 v[20:23], v[190:193], v[166:169], v[20:23]
	v_mfma_f32_16x16x32_bf16 v[16:19], v[198:201], v[166:169], v[16:19]
	v_mfma_f32_16x16x32_bf16 v[12:15], v[190:193], v[174:177], v[12:15]
	v_mfma_f32_16x16x32_bf16 v[8:11], v[198:201], v[174:177], v[8:11]
	v_mfma_f32_16x16x32_bf16 v[4:7], v[190:193], v[182:185], v[4:7]
	s_cmp_ge_u32 s54, s28
	s_mov_b32 s22, s54
	s_setprio 0
	v_mfma_f32_16x16x32_bf16 v[0:3], v[198:201], v[182:185], v[0:3]
	s_barrier
	s_cbranch_scc0 .LBB0_187
	s_branch .Lpeel_done_187
.LBB0_187:
	s_add_i32 s54, s22, 2
	s_add_u32 s23, s4, 0x4000
	s_addc_u32 s24, s5, 0
	s_cmp_eq_u32 s40, s22
	s_cselect_b32 s26, s6, s23
	s_cselect_b32 s27, s7, s24
	s_cselect_b32 s24, s20, s50
	s_cselect_b32 s25, s21, s51
	s_add_u32 s22, s26, 0x4000
	s_addc_u32 s23, s27, 0
	s_add_i32 s55, 0, 0x10000
	v_add_u32_e32 v140, s55, v207
	ds_read_b128 v[128:131], v140
	ds_read_b128 v[132:135], v140 offset:1024
	ds_read_b128 v[136:139], v140 offset:2048
	ds_read_b128 v[140:143], v140 offset:3072
	ds_read_b128 v[144:147], v209
	ds_read_b128 v[148:151], v209 offset:1024
	ds_read_b128 v[162:165], v209 offset:2048
	ds_read_b128 v[166:169], v209 offset:3072
	ds_read_b128 v[170:173], v209 offset:4096
	ds_read_b128 v[174:177], v209 offset:5120
	ds_read_b128 v[178:181], v209 offset:6144
	ds_read_b128 v[182:185], v209 offset:7168
	s_waitcnt lgkmcnt(8)
	s_barrier
	s_waitcnt lgkmcnt(0)
	v_mfma_f32_16x16x32_bf16 v[124:127], v[128:131], v[144:147], v[124:127]
	s_setprio 1
	v_mfma_f32_16x16x32_bf16 v[120:123], v[136:139], v[144:147], v[120:123]
	v_mfma_f32_16x16x32_bf16 v[116:119], v[128:131], v[162:165], v[116:119]
	s_add_i32 m0, s33, 0xc000
	v_lshl_add_u64 v[186:187], s[4:5], 0, v[158:159]
	global_load_lds_dwordx4 v[186:187], off
	v_mfma_f32_16x16x32_bf16 v[112:115], v[136:139], v[162:165], v[112:115]
	v_mfma_f32_16x16x32_bf16 v[108:111], v[128:131], v[170:173], v[108:111]
	v_mfma_f32_16x16x32_bf16 v[104:107], v[136:139], v[170:173], v[104:107]
	v_mfma_f32_16x16x32_bf16 v[100:103], v[128:131], v[178:181], v[100:103]
	s_add_i32 m0, s33, 0xe000
	v_lshl_add_u64 v[186:187], s[4:5], 0, v[160:161]
	global_load_lds_dwordx4 v[186:187], off
	v_mfma_f32_16x16x32_bf16 v[96:99], v[136:139], v[178:181], v[96:99]
	v_mfma_f32_16x16x32_bf16 v[124:127], v[132:135], v[148:151], v[124:127]
	v_mfma_f32_16x16x32_bf16 v[120:123], v[140:143], v[148:151], v[120:123]
	v_mfma_f32_16x16x32_bf16 v[116:119], v[132:135], v[166:169], v[116:119]
	v_mfma_f32_16x16x32_bf16 v[112:115], v[140:143], v[166:169], v[112:115]
	v_mfma_f32_16x16x32_bf16 v[108:111], v[132:135], v[174:177], v[108:111]
	v_mfma_f32_16x16x32_bf16 v[104:107], v[140:143], v[174:177], v[104:107]
	v_mfma_f32_16x16x32_bf16 v[100:103], v[132:135], v[182:185], v[100:103]
	s_setprio 0
	v_mfma_f32_16x16x32_bf16 v[96:99], v[140:143], v[182:185], v[96:99]
	s_barrier
	s_add_i32 s58, 0, 0x14000
	s_add_i32 s55, s55, s31
	v_add_u32_e32 v198, s58, v207
	v_lshl_add_u64 v[202:203], s[24:25], 0, v[152:153]
	s_mov_b32 m0, s55
	ds_read_b128 v[186:189], v198
	ds_read_b128 v[190:193], v198 offset:1024
	ds_read_b128 v[194:197], v198 offset:2048
	ds_read_b128 v[198:201], v198 offset:3072
	global_load_lds_dwordx4 v[202:203], off
	s_add_i32 m0, s55, 0x2000
	v_lshl_add_u64 v[202:203], s[24:25], 0, v[156:157]
	global_load_lds_dwordx4 v[202:203], off
	s_barrier
; #define PG8_STAGE(bufoff, gbase, voff) do { _Pragma("unroll") for (int _i = 0; _i < 2; ++_i) \
;         __builtin_amdgcn_global_load_lds((const unsigned*)((const char*)(gbase) + (voff)[_i]), (LAS unsigned*)(lds + (bufoff) + ldsw + _i * 8192), 16, 0, 0); } while (0)
; #define PG8_LDA(dst, b, h) do { _Pragma("unroll") for (int m = 0; m < 4; ++m) _Pragma("unroll") for (int k = 0; k < 2; ++k) dst[m][k] = *(const LAS bf16x8*)(lds + PG8_SA(b, h) + aoff + m * 2048 + k * 1024); } while (0)
; #define PG8_LDB(dst, b, h) do { _Pragma("unroll") for (int n = 0; n < 2; ++n) _Pragma("unroll") for (int k = 0; k < 2; ++k) dst[n][k] = *(const LAS bf16x8*)(lds + PG8_SB(b, h) + boff + n * 2048 + k * 1024); } while (0)
; #define PG8_MMA(ai, bj, At, Bt) do { __builtin_amdgcn_s_setprio(1); _Pragma("unroll") for (int m = 0; m < 4; ++m) _Pragma("unroll") for (int n = 0; n < 2; ++n) _Pragma("unroll") for (int k = 0; k < 2; ++k) \
;         acc[ai][bj][m][n] = __builtin_amdgcn_mfma_f32_16x16x32_bf16(Bt[n][k], At[m][k], acc[ai][bj][m][n], 0, 0, 0); __builtin_amdgcn_s_setprio(0); } while (0)
; #define PG8_WAIT_V(n) asm volatile("s_waitcnt vmcnt(" #n ")" ::: "memory")
; #define PG8_WAIT_L(n) asm volatile("s_waitcnt lgkmcnt(" #n ")" ::: "memory")
; #define PG8_BAR __builtin_amdgcn_s_barrier()
; #define PG8_SCHED __builtin_amdgcn_sched_barrier(0)
; template <class Epi>
; __device__ __forceinline__ void gemm_phase(LAS unsigned char* lds, const Gemm g, const StaticOrder& S, const Epi& E) {
;     ...
;             PG8_BAR; PG8_WAIT_L(0); PG8_MMA(0, 1, At, B1); PG8_BAR;
;             PG8_LDA(At, 0, 1); PG8_STAGE(PG8_SA(0, 0), a2, voffA);
;             PG8_BAR; PG8_WAIT_L(0); PG8_MMA(1, 0, At, B0); PG8_BAR; PG8_SCHED;
;             PG8_STAGE(PG8_SB(0, 1), b2 + hstepB, voffB);
;             PG8_WAIT_V(6); PG8_BAR; PG8_MMA(1, 1, At, B1); PG8_BAR;
;             PG8_LDB(B0, 1, 0); PG8_SCHED; PG8_LDA(At, 1, 0); PG8_STAGE(PG8_SA(0, 1), a2 + hstepA, voffA);
;             PG8_WAIT_L(8); PG8_BAR; PG8_WAIT_L(0); PG8_MMA(0, 0, At, B0); PG8_BAR; PG8_SCHED;
;             PG8_LDB(B1, 1, 1); PG8_STAGE(PG8_SB(1, 0), b3, voffB);
;             PG8_BAR; PG8_WAIT_L(0); PG8_MMA(0, 1, At, B1); PG8_BAR;
;             PG8_LDA(At, 1, 1); PG8_STAGE(PG8_SA(1, 0), a3, voffA);
	s_waitcnt lgkmcnt(0)
	v_mfma_f32_16x16x32_bf16 v[92:95], v[186:189], v[144:147], v[92:95]
	s_setprio 1
	v_mfma_f32_16x16x32_bf16 v[88:91], v[194:197], v[144:147], v[88:91]
	s_mov_b32 m0, s33
	v_lshl_add_u64 v[202:203], s[26:27], 0, v[152:153]
	v_mfma_f32_16x16x32_bf16 v[84:87], v[186:189], v[162:165], v[84:87]
	v_mfma_f32_16x16x32_bf16 v[80:83], v[194:197], v[162:165], v[80:83]
	v_mfma_f32_16x16x32_bf16 v[76:79], v[186:189], v[170:173], v[76:79]
	v_mfma_f32_16x16x32_bf16 v[72:75], v[194:197], v[170:173], v[72:75]
	v_mfma_f32_16x16x32_bf16 v[68:71], v[186:189], v[178:181], v[68:71]
	v_mfma_f32_16x16x32_bf16 v[64:67], v[194:197], v[178:181], v[64:67]
	v_mfma_f32_16x16x32_bf16 v[92:95], v[190:193], v[148:151], v[92:95]
	v_mfma_f32_16x16x32_bf16 v[88:91], v[198:201], v[148:151], v[88:91]
	v_mfma_f32_16x16x32_bf16 v[84:87], v[190:193], v[166:169], v[84:87]
	v_mfma_f32_16x16x32_bf16 v[80:83], v[198:201], v[166:169], v[80:83]
	v_mfma_f32_16x16x32_bf16 v[76:79], v[190:193], v[174:177], v[76:79]
	v_mfma_f32_16x16x32_bf16 v[72:75], v[198:201], v[174:177], v[72:75]
	v_mfma_f32_16x16x32_bf16 v[68:71], v[190:193], v[182:185], v[68:71]
	s_setprio 0
	v_mfma_f32_16x16x32_bf16 v[64:67], v[198:201], v[182:185], v[64:67]
	s_barrier
	ds_read_b128 v[144:147], v209 offset:16384
	ds_read_b128 v[148:151], v209 offset:17408
	ds_read_b128 v[162:165], v209 offset:18432
	ds_read_b128 v[166:169], v209 offset:19456
	ds_read_b128 v[170:173], v209 offset:20480
	ds_read_b128 v[174:177], v209 offset:21504
	ds_read_b128 v[178:181], v209 offset:22528
	ds_read_b128 v[182:185], v209 offset:23552
	global_load_lds_dwordx4 v[202:203], off
	s_mov_b32 m0, s34
	v_lshl_add_u64 v[202:203], s[26:27], 0, v[156:157]
	global_load_lds_dwordx4 v[202:203], off
	s_barrier
	s_waitcnt lgkmcnt(0)
	v_mfma_f32_16x16x32_bf16 v[60:63], v[128:131], v[144:147], v[60:63]
	s_setprio 1
	v_mfma_f32_16x16x32_bf16 v[56:59], v[136:139], v[144:147], v[56:59]
	v_mfma_f32_16x16x32_bf16 v[52:55], v[128:131], v[162:165], v[52:55]
	v_mfma_f32_16x16x32_bf16 v[48:51], v[136:139], v[162:165], v[48:51]
	v_mfma_f32_16x16x32_bf16 v[44:47], v[128:131], v[170:173], v[44:47]
	v_mfma_f32_16x16x32_bf16 v[40:43], v[136:139], v[170:173], v[40:43]
	v_mfma_f32_16x16x32_bf16 v[36:39], v[128:131], v[178:181], v[36:39]
	v_mfma_f32_16x16x32_bf16 v[32:35], v[136:139], v[178:181], v[32:35]
	v_mfma_f32_16x16x32_bf16 v[60:63], v[132:135], v[148:151], v[60:63]
	v_mfma_f32_16x16x32_bf16 v[56:59], v[140:143], v[148:151], v[56:59]
	v_mfma_f32_16x16x32_bf16 v[52:55], v[132:135], v[166:169], v[52:55]
	v_mfma_f32_16x16x32_bf16 v[48:51], v[140:143], v[166:169], v[48:51]
	v_mfma_f32_16x16x32_bf16 v[44:47], v[132:135], v[174:177], v[44:47]
	v_mfma_f32_16x16x32_bf16 v[40:43], v[140:143], v[174:177], v[40:43]
	v_mfma_f32_16x16x32_bf16 v[36:39], v[132:135], v[182:185], v[36:39]
	s_setprio 0
	v_mfma_f32_16x16x32_bf16 v[32:35], v[140:143], v[182:185], v[32:35]
	s_barrier
	s_add_u32 s56, s24, s52
	s_addc_u32 s57, s25, 0
	s_add_i32 s55, s58, s31
	s_mov_b32 m0, s55
	v_lshl_add_u64 v[128:129], s[56:57], 0, v[152:153]
	global_load_lds_dwordx4 v[128:129], off
	s_add_i32 m0, s55, 0x2000
	v_lshl_add_u64 v[128:129], s[56:57], 0, v[156:157]
	global_load_lds_dwordx4 v[128:129], off
	s_waitcnt vmcnt(6)
	s_barrier
	v_mfma_f32_16x16x32_bf16 v[28:31], v[186:189], v[144:147], v[28:31]
	s_setprio 1
	v_mfma_f32_16x16x32_bf16 v[24:27], v[194:197], v[144:147], v[24:27]
	s_add_i32 s55, 0, 0x18000
	v_add_u32_e32 v140, s55, v207
	v_mfma_f32_16x16x32_bf16 v[20:23], v[186:189], v[162:165], v[20:23]
	v_mfma_f32_16x16x32_bf16 v[16:19], v[194:197], v[162:165], v[16:19]
	v_mfma_f32_16x16x32_bf16 v[12:15], v[186:189], v[170:173], v[12:15]
	v_mfma_f32_16x16x32_bf16 v[8:11], v[194:197], v[170:173], v[8:11]
	v_mfma_f32_16x16x32_bf16 v[4:7], v[186:189], v[178:181], v[4:7]
	v_mfma_f32_16x16x32_bf16 v[0:3], v[194:197], v[178:181], v[0:3]
	v_mfma_f32_16x16x32_bf16 v[28:31], v[190:193], v[148:151], v[28:31]
	v_mfma_f32_16x16x32_bf16 v[24:27], v[198:201], v[148:151], v[24:27]
	v_mfma_f32_16x16x32_bf16 v[20:23], v[190:193], v[166:169], v[20:23]
	v_mfma_f32_16x16x32_bf16 v[16:19], v[198:201], v[166:169], v[16:19]
	v_mfma_f32_16x16x32_bf16 v[12:15], v[190:193], v[174:177], v[12:15]
	v_mfma_f32_16x16x32_bf16 v[8:11], v[198:201], v[174:177], v[8:11]
	v_mfma_f32_16x16x32_bf16 v[4:7], v[190:193], v[182:185], v[4:7]
	s_setprio 0
	v_mfma_f32_16x16x32_bf16 v[0:3], v[198:201], v[182:185], v[0:3]
	s_barrier
	ds_read_b128 v[128:131], v140
	ds_read_b128 v[132:135], v140 offset:1024
	ds_read_b128 v[136:139], v140 offset:2048
	ds_read_b128 v[140:143], v140 offset:3072
	s_add_u32 s26, s26, s52
	s_addc_u32 s27, s27, 0
	ds_read_b128 v[144:147], v209 offset:32768
	ds_read_b128 v[148:151], v209 offset:33792
	ds_read_b128 v[162:165], v209 offset:34816
	ds_read_b128 v[166:169], v209 offset:35840
	ds_read_b128 v[170:173], v209 offset:36864
	ds_read_b128 v[174:177], v209 offset:37888
	ds_read_b128 v[178:181], v209 offset:38912
	ds_read_b128 v[182:185], v209 offset:39936
	s_waitcnt lgkmcnt(8)
	s_barrier
; #define PG8_STAGE(bufoff, gbase, voff) do { _Pragma("unroll") for (int _i = 0; _i < 2; ++_i) \
;         __builtin_amdgcn_global_load_lds((const unsigned*)((const char*)(gbase) + (voff)[_i]), (LAS unsigned*)(lds + (bufoff) + ldsw + _i * 8192), 16, 0, 0); } while (0)
; #define PG8_LDA(dst, b, h) do { _Pragma("unroll") for (int m = 0; m < 4; ++m) _Pragma("unroll") for (int k = 0; k < 2; ++k) dst[m][k] = *(const LAS bf16x8*)(lds + PG8_SA(b, h) + aoff + m * 2048 + k * 1024); } while (0)
; #define PG8_LDB(dst, b, h) do { _Pragma("unroll") for (int n = 0; n < 2; ++n) _Pragma("unroll") for (int k = 0; k < 2; ++k) dst[n][k] = *(const LAS bf16x8*)(lds + PG8_SB(b, h) + boff + n * 2048 + k * 1024); } while (0)
; #define PG8_MMA(ai, bj, At, Bt) do { __builtin_amdgcn_s_setprio(1); _Pragma("unroll") for (int m = 0; m < 4; ++m) _Pragma("unroll") for (int n = 0; n < 2; ++n) _Pragma("unroll") for (int k = 0; k < 2; ++k) \
;         acc[ai][bj][m][n] = __builtin_amdgcn_mfma_f32_16x16x32_bf16(Bt[n][k], At[m][k], acc[ai][bj][m][n], 0, 0, 0); __builtin_amdgcn_s_setprio(0); } while (0)
; #define PG8_WAIT_V(n) asm volatile("s_waitcnt vmcnt(" #n ")" ::: "memory")
; #define PG8_WAIT_L(n) asm volatile("s_waitcnt lgkmcnt(" #n ")" ::: "memory")
; #define PG8_BAR __builtin_amdgcn_s_barrier()
; #define PG8_SCHED __builtin_amdgcn_sched_barrier(0)
; template <class Epi>
; __device__ __forceinline__ void gemm_phase(LAS unsigned char* lds, const Gemm g, const StaticOrder& S, const Epi& E) {
;     ...
;             PG8_LDB(B0, 1, 0); PG8_SCHED; PG8_LDA(At, 1, 0); PG8_STAGE(PG8_SA(0, 1), a2 + hstepA, voffA);
;             PG8_WAIT_L(8); PG8_BAR; PG8_WAIT_L(0); PG8_MMA(0, 0, At, B0); PG8_BAR; PG8_SCHED;
;             PG8_LDB(B1, 1, 1); PG8_STAGE(PG8_SB(1, 0), b3, voffB);
;             PG8_BAR; PG8_WAIT_L(0); PG8_MMA(0, 1, At, B1); PG8_BAR;
;             PG8_LDA(At, 1, 1); PG8_STAGE(PG8_SA(1, 0), a3, voffA);
;             PG8_BAR; PG8_WAIT_L(0); PG8_MMA(1, 0, At, B0); PG8_BAR; PG8_SCHED;
;             PG8_STAGE(PG8_SB(1, 1), b3 + hstepB, voffB);
;             PG8_WAIT_V(6); PG8_BAR; PG8_MMA(1, 1, At, B1); PG8_BAR;
	s_waitcnt lgkmcnt(0)
	v_mfma_f32_16x16x32_bf16 v[124:127], v[128:131], v[144:147], v[124:127]
	s_setprio 1
	v_mfma_f32_16x16x32_bf16 v[120:123], v[136:139], v[144:147], v[120:123]
	v_mfma_f32_16x16x32_bf16 v[116:119], v[128:131], v[162:165], v[116:119]
	s_mov_b32 m0, s35
	v_lshl_add_u64 v[186:187], s[26:27], 0, v[152:153]
	global_load_lds_dwordx4 v[186:187], off
	v_mfma_f32_16x16x32_bf16 v[112:115], v[136:139], v[162:165], v[112:115]
	v_mfma_f32_16x16x32_bf16 v[108:111], v[128:131], v[170:173], v[108:111]
	v_mfma_f32_16x16x32_bf16 v[104:107], v[136:139], v[170:173], v[104:107]
	v_mfma_f32_16x16x32_bf16 v[100:103], v[128:131], v[178:181], v[100:103]
	s_mov_b32 m0, s36
	v_lshl_add_u64 v[186:187], s[26:27], 0, v[156:157]
	global_load_lds_dwordx4 v[186:187], off
	v_mfma_f32_16x16x32_bf16 v[96:99], v[136:139], v[178:181], v[96:99]
	v_mfma_f32_16x16x32_bf16 v[124:127], v[132:135], v[148:151], v[124:127]
	v_mfma_f32_16x16x32_bf16 v[120:123], v[140:143], v[148:151], v[120:123]
	v_mfma_f32_16x16x32_bf16 v[116:119], v[132:135], v[166:169], v[116:119]
	v_mfma_f32_16x16x32_bf16 v[112:115], v[140:143], v[166:169], v[112:115]
	v_mfma_f32_16x16x32_bf16 v[108:111], v[132:135], v[174:177], v[108:111]
	v_mfma_f32_16x16x32_bf16 v[104:107], v[140:143], v[174:177], v[104:107]
	v_mfma_f32_16x16x32_bf16 v[100:103], v[132:135], v[182:185], v[100:103]
	s_setprio 0
	v_mfma_f32_16x16x32_bf16 v[96:99], v[140:143], v[182:185], v[96:99]
	s_barrier
	s_add_i32 s26, 0, 0x1c000
	s_add_u32 s24, s24, 0x4000
	s_addc_u32 s25, s25, 0
	s_add_i32 s27, s55, s31
	v_add_u32_e32 v198, s26, v207
	v_lshl_add_u64 v[202:203], s[24:25], 0, v[152:153]
	s_mov_b32 m0, s27
	ds_read_b128 v[186:189], v198
	ds_read_b128 v[190:193], v198 offset:1024
	ds_read_b128 v[194:197], v198 offset:2048
	ds_read_b128 v[198:201], v198 offset:3072
	global_load_lds_dwordx4 v[202:203], off
	s_add_i32 m0, s27, 0x2000
	v_lshl_add_u64 v[202:203], s[24:25], 0, v[156:157]
	global_load_lds_dwordx4 v[202:203], off
	s_barrier
	s_waitcnt lgkmcnt(0)
	v_mfma_f32_16x16x32_bf16 v[92:95], v[186:189], v[144:147], v[92:95]
	s_setprio 1
	v_mfma_f32_16x16x32_bf16 v[88:91], v[194:197], v[144:147], v[88:91]
	s_mov_b32 m0, s38
	v_lshl_add_u64 v[202:203], s[22:23], 0, v[152:153]
	v_mfma_f32_16x16x32_bf16 v[84:87], v[186:189], v[162:165], v[84:87]
	v_mfma_f32_16x16x32_bf16 v[80:83], v[194:197], v[162:165], v[80:83]
	v_mfma_f32_16x16x32_bf16 v[76:79], v[186:189], v[170:173], v[76:79]
	v_mfma_f32_16x16x32_bf16 v[72:75], v[194:197], v[170:173], v[72:75]
	v_mfma_f32_16x16x32_bf16 v[68:71], v[186:189], v[178:181], v[68:71]
	v_mfma_f32_16x16x32_bf16 v[64:67], v[194:197], v[178:181], v[64:67]
	v_mfma_f32_16x16x32_bf16 v[92:95], v[190:193], v[148:151], v[92:95]
	v_mfma_f32_16x16x32_bf16 v[88:91], v[198:201], v[148:151], v[88:91]
	v_mfma_f32_16x16x32_bf16 v[84:87], v[190:193], v[166:169], v[84:87]
	v_mfma_f32_16x16x32_bf16 v[80:83], v[198:201], v[166:169], v[80:83]
	v_mfma_f32_16x16x32_bf16 v[76:79], v[190:193], v[174:177], v[76:79]
	v_mfma_f32_16x16x32_bf16 v[72:75], v[198:201], v[174:177], v[72:75]
	v_mfma_f32_16x16x32_bf16 v[68:71], v[190:193], v[182:185], v[68:71]
	s_setprio 0
	v_mfma_f32_16x16x32_bf16 v[64:67], v[198:201], v[182:185], v[64:67]
	s_barrier
	ds_read_b128 v[144:147], v209 offset:49152
	ds_read_b128 v[148:151], v209 offset:50176
	ds_read_b128 v[162:165], v209 offset:51200
	ds_read_b128 v[166:169], v209 offset:52224
	ds_read_b128 v[170:173], v209 offset:53248
	ds_read_b128 v[174:177], v209 offset:54272
	ds_read_b128 v[178:181], v209 offset:55296
	ds_read_b128 v[182:185], v209 offset:56320
	global_load_lds_dwordx4 v[202:203], off
	s_mov_b32 m0, s39
	v_lshl_add_u64 v[202:203], s[22:23], 0, v[156:157]
	global_load_lds_dwordx4 v[202:203], off
	s_barrier
	s_waitcnt lgkmcnt(0)
	v_mfma_f32_16x16x32_bf16 v[60:63], v[128:131], v[144:147], v[60:63]
	s_setprio 1
	v_mfma_f32_16x16x32_bf16 v[56:59], v[136:139], v[144:147], v[56:59]
	v_mfma_f32_16x16x32_bf16 v[52:55], v[128:131], v[162:165], v[52:55]
	v_mfma_f32_16x16x32_bf16 v[48:51], v[136:139], v[162:165], v[48:51]
	v_mfma_f32_16x16x32_bf16 v[44:47], v[128:131], v[170:173], v[44:47]
	v_mfma_f32_16x16x32_bf16 v[40:43], v[136:139], v[170:173], v[40:43]
	v_mfma_f32_16x16x32_bf16 v[36:39], v[128:131], v[178:181], v[36:39]
	v_mfma_f32_16x16x32_bf16 v[32:35], v[136:139], v[178:181], v[32:35]
	v_mfma_f32_16x16x32_bf16 v[60:63], v[132:135], v[148:151], v[60:63]
	v_mfma_f32_16x16x32_bf16 v[56:59], v[140:143], v[148:151], v[56:59]
	v_mfma_f32_16x16x32_bf16 v[52:55], v[132:135], v[166:169], v[52:55]
	v_mfma_f32_16x16x32_bf16 v[48:51], v[140:143], v[166:169], v[48:51]
	v_mfma_f32_16x16x32_bf16 v[44:47], v[132:135], v[174:177], v[44:47]
	v_mfma_f32_16x16x32_bf16 v[40:43], v[140:143], v[174:177], v[40:43]
	v_mfma_f32_16x16x32_bf16 v[36:39], v[132:135], v[182:185], v[36:39]
	s_setprio 0
	v_mfma_f32_16x16x32_bf16 v[32:35], v[140:143], v[182:185], v[32:35]
	s_barrier
	s_add_u32 s22, s24, s52
	s_addc_u32 s23, s25, 0
	s_add_i32 s24, s26, s31
	s_mov_b32 m0, s24
	v_lshl_add_u64 v[128:129], s[22:23], 0, v[152:153]
	global_load_lds_dwordx4 v[128:129], off
	s_add_i32 m0, s24, 0x2000
	v_lshl_add_u64 v[128:129], s[22:23], 0, v[156:157]
	global_load_lds_dwordx4 v[128:129], off
	s_waitcnt vmcnt(6)
	s_barrier
	v_mfma_f32_16x16x32_bf16 v[28:31], v[186:189], v[144:147], v[28:31]
	s_setprio 1
	v_mfma_f32_16x16x32_bf16 v[24:27], v[194:197], v[144:147], v[24:27]
	s_add_u32 s4, s4, 0x8000
	s_addc_u32 s5, s5, 0
	s_add_u32 s50, s50, 0x8000
	s_addc_u32 s51, s51, 0
	v_mfma_f32_16x16x32_bf16 v[20:23], v[186:189], v[162:165], v[20:23]
	v_mfma_f32_16x16x32_bf16 v[16:19], v[194:197], v[162:165], v[16:19]
	v_mfma_f32_16x16x32_bf16 v[12:15], v[186:189], v[170:173], v[12:15]
	v_mfma_f32_16x16x32_bf16 v[8:11], v[194:197], v[170:173], v[8:11]
	v_mfma_f32_16x16x32_bf16 v[4:7], v[186:189], v[178:181], v[4:7]
	v_mfma_f32_16x16x32_bf16 v[0:3], v[194:197], v[178:181], v[0:3]
	v_mfma_f32_16x16x32_bf16 v[28:31], v[190:193], v[148:151], v[28:31]
	v_mfma_f32_16x16x32_bf16 v[24:27], v[198:201], v[148:151], v[24:27]
	v_mfma_f32_16x16x32_bf16 v[20:23], v[190:193], v[166:169], v[20:23]
	v_mfma_f32_16x16x32_bf16 v[16:19], v[198:201], v[166:169], v[16:19]
	v_mfma_f32_16x16x32_bf16 v[12:15], v[190:193], v[174:177], v[12:15]
	v_mfma_f32_16x16x32_bf16 v[8:11], v[198:201], v[174:177], v[8:11]
	v_mfma_f32_16x16x32_bf16 v[4:7], v[190:193], v[182:185], v[4:7]
	s_cmp_ge_u32 s54, s28
	s_mov_b32 s22, s54
	s_setprio 0
	v_mfma_f32_16x16x32_bf16 v[0:3], v[198:201], v[182:185], v[0:3]
	s_barrier
	s_cbranch_scc0 .LBB0_187

; #define PG8_STAGE(bufoff, gbase, voff) do { _Pragma("unroll") for (int _i = 0; _i < 2; ++_i) \
;         __builtin_amdgcn_global_load_lds((const unsigned*)((const char*)(gbase) + (voff)[_i]), (LAS unsigned*)(lds + (bufoff) + ldsw + _i * 8192), 16, 0, 0); } while (0)
; #define PG8_WAIT_V(n) asm volatile("s_waitcnt vmcnt(" #n ")" ::: "memory")
; #define PG8_WAIT_L(n) asm volatile("s_waitcnt lgkmcnt(" #n ")" ::: "memory")
; template <class Epi>
; __device__ __forceinline__ void gemm_phase(LAS unsigned char* lds, const Gemm g, const StaticOrder& S, const Epi& E) {
;     ...
;         const bool has_next = S.next(ui + 1, nxt);
;         const char* nA = has_next ? (const char*)g.A + (size_t)nxt.pm * tstepA : cA; const char* nB = has_next ? (const char*)g.Bt + (size_t)nxt.pn * tstepB : cB;
;         for (int t = 0; t < nt; t += 2) {
;             const bool last = (t == nt - 2);
;             const char* a1 = cA + (size_t)(t + 1) * kstep;
;             const char* a2 = last ? nA : cA + (size_t)(t + 2) * kstep; const char* b2 = last ? nB : cB + (size_t)(t + 2) * kstep;
;             const char* a3 = a2 + kstep; const char* b3 = b2 + kstep;
;             PG8_LDB(B0, 0, 0); PG8_SCHED; PG8_LDA(At, 0, 0); PG8_STAGE(PG8_SA(1, 1), a1 + hstepA, voffA);
;             PG8_WAIT_L(8); PG8_BAR; PG8_WAIT_L(0); PG8_MMA(0, 0, At, B0); PG8_BAR; PG8_SCHED;
;             PG8_LDB(B1, 0, 1); PG8_STAGE(PG8_SB(0, 0), b2, voffB);
;             PG8_BAR; PG8_WAIT_L(0); PG8_MMA(0, 1, At, B1); PG8_BAR;
;             PG8_LDA(At, 0, 1); PG8_STAGE(PG8_SA(0, 0), a2, voffA);
;             PG8_BAR; PG8_WAIT_L(0); PG8_MMA(1, 0, At, B0); PG8_BAR; PG8_SCHED;
;             PG8_STAGE(PG8_SB(0, 1), b2 + hstepB, voffB);
;             PG8_WAIT_V(6); PG8_BAR; PG8_MMA(1, 1, At, B1); PG8_BAR;
;             PG8_LDB(B0, 1, 0); PG8_SCHED; PG8_LDA(At, 1, 0); PG8_STAGE(PG8_SA(0, 1), a2 + hstepA, voffA);
;             PG8_WAIT_L(8); PG8_BAR; PG8_WAIT_L(0); PG8_MMA(0, 0, At, B0); PG8_BAR; PG8_SCHED;
;             PG8_LDB(B1, 1, 1); PG8_STAGE(PG8_SB(1, 0), b3, voffB);
;             PG8_BAR; PG8_WAIT_L(0); PG8_MMA(0, 1, At, B1); PG8_BAR;
;             PG8_LDA(At, 1, 1); PG8_STAGE(PG8_SA(1, 0), a3, voffA);
;             PG8_BAR; PG8_WAIT_L(0); PG8_MMA(1, 0, At, B0); PG8_BAR; PG8_SCHED;
;             PG8_STAGE(PG8_SB(1, 1), b3 + hstepB, voffB);
;             PG8_WAIT_V(6); PG8_BAR; PG8_MMA(1, 1, At, B1); PG8_BAR;
.LBB0_246:
	s_ashr_i32 s5, s4, 31
	v_cmp_lt_i64_e32 vcc, s[6:7], v[154:155]
	s_lshl_b64 s[6:7], s[4:5], 20
	v_readlane_b32 s8, v252, 53
	v_readlane_b32 s9, v252, 54
	s_add_u32 s6, s8, s6
	s_addc_u32 s7, s9, s7
	s_and_b64 s[8:9], vcc, exec
	s_cselect_b32 s5, s7, s13
	s_cselect_b32 s11, s6, s12
	s_ashr_i32 s3, s2, 31
	s_lshl_b64 s[8:9], s[2:3], 20
	s_add_u32 s8, s21, s8
	s_addc_u32 s9, s22, s9
	s_and_b64 s[16:17], vcc, exec
	s_cselect_b32 s3, s9, s15
	s_cselect_b32 s35, s8, s14
	s_add_u32 s12, s12, 0x84000
	s_addc_u32 s13, s13, 0
	s_add_u32 s36, s14, 0x8000
	s_addc_u32 s37, s15, 0
	s_mov_b32 s38, -2
	s_add_u32 s14, s12, 0xfff84000
	s_addc_u32 s15, s13, -1
	s_cmp_eq_u32 s38, 28
	s_cselect_b32 s18, s11, s14
	s_cselect_b32 s19, s5, s15
	s_cselect_b32 s14, s35, s36
	s_cselect_b32 s15, s3, s37
	s_add_u32 s16, s18, 0x4000
	s_addc_u32 s17, s19, 0
	s_add_i32 s39, 0, 0x10000
	v_add_u32_e32 v140, s39, v170
	ds_read_b128 v[128:131], v140
	ds_read_b128 v[132:135], v140 offset:1024
	ds_read_b128 v[136:139], v140 offset:2048
	ds_read_b128 v[140:143], v140 offset:3072
	ds_read_b128 v[144:147], v172
	ds_read_b128 v[148:151], v172 offset:1024
	ds_read_b128 v[166:169], v172 offset:2048
	ds_read_b128 v[174:177], v172 offset:3072
	ds_read_b128 v[178:181], v172 offset:4096
	ds_read_b128 v[182:185], v172 offset:5120
	ds_read_b128 v[186:189], v172 offset:6144
	ds_read_b128 v[190:193], v172 offset:7168
	s_waitcnt lgkmcnt(8)
	s_barrier
	s_waitcnt lgkmcnt(0)
	v_mfma_f32_16x16x32_bf16 v[124:127], v[128:131], v[144:147], 0
	s_setprio 1
	v_mfma_f32_16x16x32_bf16 v[120:123], v[136:139], v[144:147], 0
	v_mfma_f32_16x16x32_bf16 v[108:111], v[128:131], v[166:169], 0
	s_add_i32 m0, s25, 0xc000
	v_lshl_add_u64 v[194:195], s[12:13], 0, v[156:157]
	global_load_lds_dwordx4 v[194:195], off
	v_mfma_f32_16x16x32_bf16 v[104:107], v[136:139], v[166:169], 0
	v_mfma_f32_16x16x32_bf16 v[92:95], v[128:131], v[178:181], 0
	v_mfma_f32_16x16x32_bf16 v[88:91], v[136:139], v[178:181], 0
	v_mfma_f32_16x16x32_bf16 v[76:79], v[128:131], v[186:189], 0
	s_add_i32 m0, s25, 0xe000
	v_lshl_add_u64 v[194:195], s[12:13], 0, v[158:159]
	global_load_lds_dwordx4 v[194:195], off
	v_mfma_f32_16x16x32_bf16 v[72:75], v[136:139], v[186:189], 0
	v_mfma_f32_16x16x32_bf16 v[124:127], v[132:135], v[148:151], v[124:127]
	v_mfma_f32_16x16x32_bf16 v[120:123], v[140:143], v[148:151], v[120:123]
	v_mfma_f32_16x16x32_bf16 v[108:111], v[132:135], v[174:177], v[108:111]
	v_mfma_f32_16x16x32_bf16 v[104:107], v[140:143], v[174:177], v[104:107]
	v_mfma_f32_16x16x32_bf16 v[92:95], v[132:135], v[182:185], v[92:95]
	v_mfma_f32_16x16x32_bf16 v[88:91], v[140:143], v[182:185], v[88:91]
	v_mfma_f32_16x16x32_bf16 v[76:79], v[132:135], v[190:193], v[76:79]
	s_setprio 0
	v_mfma_f32_16x16x32_bf16 v[72:75], v[140:143], v[190:193], v[72:75]
	s_barrier
	s_add_i32 s42, 0, 0x14000
	s_add_i32 s39, s39, s23
	v_add_u32_e32 v152, s42, v170
	v_lshl_add_u64 v[210:211], s[14:15], 0, v[156:157]
	s_mov_b32 m0, s39
	ds_read_b128 v[194:197], v152
	ds_read_b128 v[198:201], v152 offset:1024
	ds_read_b128 v[202:205], v152 offset:2048
	ds_read_b128 v[206:209], v152 offset:3072
	global_load_lds_dwordx4 v[210:211], off
	s_add_i32 m0, s39, 0x2000
	v_lshl_add_u64 v[210:211], s[14:15], 0, v[158:159]
	global_load_lds_dwordx4 v[210:211], off
	s_barrier
	s_waitcnt lgkmcnt(0)
	v_mfma_f32_16x16x32_bf16 v[116:119], v[194:197], v[144:147], 0
	s_setprio 1
	v_mfma_f32_16x16x32_bf16 v[112:115], v[202:205], v[144:147], 0
	s_mov_b32 m0, s25
	v_lshl_add_u64 v[210:211], s[18:19], 0, v[156:157]
	v_mfma_f32_16x16x32_bf16 v[100:103], v[194:197], v[166:169], 0
	v_mfma_f32_16x16x32_bf16 v[96:99], v[202:205], v[166:169], 0
	v_mfma_f32_16x16x32_bf16 v[84:87], v[194:197], v[178:181], 0
	v_mfma_f32_16x16x32_bf16 v[80:83], v[202:205], v[178:181], 0
	v_mfma_f32_16x16x32_bf16 v[68:71], v[194:197], v[186:189], 0
	v_mfma_f32_16x16x32_bf16 v[64:67], v[202:205], v[186:189], 0
	v_mfma_f32_16x16x32_bf16 v[116:119], v[198:201], v[148:151], v[116:119]
	v_mfma_f32_16x16x32_bf16 v[112:115], v[206:209], v[148:151], v[112:115]
	v_mfma_f32_16x16x32_bf16 v[100:103], v[198:201], v[174:177], v[100:103]
	v_mfma_f32_16x16x32_bf16 v[96:99], v[206:209], v[174:177], v[96:99]
	v_mfma_f32_16x16x32_bf16 v[84:87], v[198:201], v[182:185], v[84:87]
	v_mfma_f32_16x16x32_bf16 v[80:83], v[206:209], v[182:185], v[80:83]
	v_mfma_f32_16x16x32_bf16 v[68:71], v[198:201], v[190:193], v[68:71]
	s_setprio 0
	v_mfma_f32_16x16x32_bf16 v[64:67], v[206:209], v[190:193], v[64:67]
	s_barrier
	ds_read_b128 v[144:147], v172 offset:16384
	ds_read_b128 v[148:151], v172 offset:17408
	ds_read_b128 v[166:169], v172 offset:18432
	ds_read_b128 v[174:177], v172 offset:19456
	ds_read_b128 v[178:181], v172 offset:20480
	ds_read_b128 v[182:185], v172 offset:21504
	ds_read_b128 v[186:189], v172 offset:22528
	ds_read_b128 v[190:193], v172 offset:23552
	global_load_lds_dwordx4 v[210:211], off
	s_mov_b32 m0, s26
	v_lshl_add_u64 v[210:211], s[18:19], 0, v[158:159]
	global_load_lds_dwordx4 v[210:211], off
	s_barrier
	s_waitcnt lgkmcnt(0)
	v_mfma_f32_16x16x32_bf16 v[60:63], v[128:131], v[144:147], 0
	s_setprio 1
	v_mfma_f32_16x16x32_bf16 v[56:59], v[136:139], v[144:147], 0
	v_mfma_f32_16x16x32_bf16 v[44:47], v[128:131], v[166:169], 0
	v_mfma_f32_16x16x32_bf16 v[40:43], v[136:139], v[166:169], 0
	v_mfma_f32_16x16x32_bf16 v[28:31], v[128:131], v[178:181], 0
	v_mfma_f32_16x16x32_bf16 v[24:27], v[136:139], v[178:181], 0
	v_mfma_f32_16x16x32_bf16 v[12:15], v[128:131], v[186:189], 0
	v_mfma_f32_16x16x32_bf16 v[8:11], v[136:139], v[186:189], 0
	v_mfma_f32_16x16x32_bf16 v[60:63], v[132:135], v[148:151], v[60:63]
	v_mfma_f32_16x16x32_bf16 v[56:59], v[140:143], v[148:151], v[56:59]
	v_mfma_f32_16x16x32_bf16 v[44:47], v[132:135], v[174:177], v[44:47]
	v_mfma_f32_16x16x32_bf16 v[40:43], v[140:143], v[174:177], v[40:43]
	v_mfma_f32_16x16x32_bf16 v[28:31], v[132:135], v[182:185], v[28:31]
	v_mfma_f32_16x16x32_bf16 v[24:27], v[140:143], v[182:185], v[24:27]
	v_mfma_f32_16x16x32_bf16 v[12:15], v[132:135], v[190:193], v[12:15]
	s_setprio 0
	v_mfma_f32_16x16x32_bf16 v[8:11], v[140:143], v[190:193], v[8:11]
	s_barrier
; #define PG8_STAGE(bufoff, gbase, voff) do { _Pragma("unroll") for (int _i = 0; _i < 2; ++_i) \
;         __builtin_amdgcn_global_load_lds((const unsigned*)((const char*)(gbase) + (voff)[_i]), (LAS unsigned*)(lds + (bufoff) + ldsw + _i * 8192), 16, 0, 0); } while (0)
; #define PG8_LDA(dst, b, h) do { _Pragma("unroll") for (int m = 0; m < 4; ++m) _Pragma("unroll") for (int k = 0; k < 2; ++k) dst[m][k] = *(const LAS bf16x8*)(lds + PG8_SA(b, h) + aoff + m * 2048 + k * 1024); } while (0)
; #define PG8_LDB(dst, b, h) do { _Pragma("unroll") for (int n = 0; n < 2; ++n) _Pragma("unroll") for (int k = 0; k < 2; ++k) dst[n][k] = *(const LAS bf16x8*)(lds + PG8_SB(b, h) + boff + n * 2048 + k * 1024); } while (0)
; #define PG8_MMA(ai, bj, At, Bt) do { __builtin_amdgcn_s_setprio(1); _Pragma("unroll") for (int m = 0; m < 4; ++m) _Pragma("unroll") for (int n = 0; n < 2; ++n) _Pragma("unroll") for (int k = 0; k < 2; ++k) \
;         acc[ai][bj][m][n] = __builtin_amdgcn_mfma_f32_16x16x32_bf16(Bt[n][k], At[m][k], acc[ai][bj][m][n], 0, 0, 0); __builtin_amdgcn_s_setprio(0); } while (0)
; #define PG8_WAIT_V(n) asm volatile("s_waitcnt vmcnt(" #n ")" ::: "memory")
; #define PG8_WAIT_L(n) asm volatile("s_waitcnt lgkmcnt(" #n ")" ::: "memory")
; #define PG8_BAR __builtin_amdgcn_s_barrier()
; #define PG8_SCHED __builtin_amdgcn_sched_barrier(0)
; template <class Epi>
; __device__ __forceinline__ void gemm_phase(LAS unsigned char* lds, const Gemm g, const StaticOrder& S, const Epi& E) {
;     ...
;             PG8_WAIT_V(6); PG8_BAR; PG8_MMA(1, 1, At, B1); PG8_BAR;
;             PG8_LDB(B0, 1, 0); PG8_SCHED; PG8_LDA(At, 1, 0); PG8_STAGE(PG8_SA(0, 1), a2 + hstepA, voffA);
;             PG8_WAIT_L(8); PG8_BAR; PG8_WAIT_L(0); PG8_MMA(0, 0, At, B0); PG8_BAR; PG8_SCHED;
;             PG8_LDB(B1, 1, 1); PG8_STAGE(PG8_SB(1, 0), b3, voffB);
;             PG8_BAR; PG8_WAIT_L(0); PG8_MMA(0, 1, At, B1); PG8_BAR;
;             PG8_LDA(At, 1, 1); PG8_STAGE(PG8_SA(1, 0), a3, voffA);
;             PG8_BAR; PG8_WAIT_L(0); PG8_MMA(1, 0, At, B0); PG8_BAR; PG8_SCHED;
;             PG8_STAGE(PG8_SB(1, 1), b3 + hstepB, voffB);
;             PG8_WAIT_V(6); PG8_BAR; PG8_MMA(1, 1, At, B1); PG8_BAR;
	s_add_u32 s40, s14, 0x80000
	s_addc_u32 s41, s15, 0
	s_add_i32 s39, s42, s23
	s_mov_b32 m0, s39
	v_lshl_add_u64 v[128:129], s[40:41], 0, v[156:157]
	global_load_lds_dwordx4 v[128:129], off
	s_add_i32 m0, s39, 0x2000
	v_lshl_add_u64 v[128:129], s[40:41], 0, v[158:159]
	global_load_lds_dwordx4 v[128:129], off
	s_waitcnt vmcnt(6)
	s_barrier
	v_mfma_f32_16x16x32_bf16 v[52:55], v[194:197], v[144:147], 0
	s_setprio 1
	v_mfma_f32_16x16x32_bf16 v[48:51], v[202:205], v[144:147], 0
	s_add_i32 s39, 0, 0x18000
	v_add_u32_e32 v140, s39, v170
	v_mfma_f32_16x16x32_bf16 v[36:39], v[194:197], v[166:169], 0
	v_mfma_f32_16x16x32_bf16 v[32:35], v[202:205], v[166:169], 0
	v_mfma_f32_16x16x32_bf16 v[20:23], v[194:197], v[178:181], 0
	v_mfma_f32_16x16x32_bf16 v[16:19], v[202:205], v[178:181], 0
	v_mfma_f32_16x16x32_bf16 v[4:7], v[194:197], v[186:189], 0
	v_mfma_f32_16x16x32_bf16 v[0:3], v[202:205], v[186:189], 0
	v_mfma_f32_16x16x32_bf16 v[52:55], v[198:201], v[148:151], v[52:55]
	v_mfma_f32_16x16x32_bf16 v[48:51], v[206:209], v[148:151], v[48:51]
	v_mfma_f32_16x16x32_bf16 v[36:39], v[198:201], v[174:177], v[36:39]
	v_mfma_f32_16x16x32_bf16 v[32:35], v[206:209], v[174:177], v[32:35]
	v_mfma_f32_16x16x32_bf16 v[20:23], v[198:201], v[182:185], v[20:23]
	v_mfma_f32_16x16x32_bf16 v[16:19], v[206:209], v[182:185], v[16:19]
	v_mfma_f32_16x16x32_bf16 v[4:7], v[198:201], v[190:193], v[4:7]
	s_setprio 0
	v_mfma_f32_16x16x32_bf16 v[0:3], v[206:209], v[190:193], v[0:3]
	s_barrier
	ds_read_b128 v[128:131], v140
	ds_read_b128 v[132:135], v140 offset:1024
	ds_read_b128 v[136:139], v140 offset:2048
	ds_read_b128 v[140:143], v140 offset:3072
	s_add_u32 s18, s18, 0x80000
	s_addc_u32 s19, s19, 0
	ds_read_b128 v[144:147], v172 offset:32768
	ds_read_b128 v[148:151], v172 offset:33792
	ds_read_b128 v[166:169], v172 offset:34816
	ds_read_b128 v[174:177], v172 offset:35840
	ds_read_b128 v[178:181], v172 offset:36864
	ds_read_b128 v[182:185], v172 offset:37888
	ds_read_b128 v[186:189], v172 offset:38912
	ds_read_b128 v[190:193], v172 offset:39936
	s_waitcnt lgkmcnt(8)
	s_barrier
	s_waitcnt lgkmcnt(0)
	v_mfma_f32_16x16x32_bf16 v[124:127], v[128:131], v[144:147], v[124:127]
	s_setprio 1
	v_mfma_f32_16x16x32_bf16 v[120:123], v[136:139], v[144:147], v[120:123]
	v_mfma_f32_16x16x32_bf16 v[108:111], v[128:131], v[166:169], v[108:111]
	s_mov_b32 m0, s27
	v_lshl_add_u64 v[194:195], s[18:19], 0, v[156:157]
	global_load_lds_dwordx4 v[194:195], off
	v_mfma_f32_16x16x32_bf16 v[104:107], v[136:139], v[166:169], v[104:107]
	v_mfma_f32_16x16x32_bf16 v[92:95], v[128:131], v[178:181], v[92:95]
	v_mfma_f32_16x16x32_bf16 v[88:91], v[136:139], v[178:181], v[88:91]
	v_mfma_f32_16x16x32_bf16 v[76:79], v[128:131], v[186:189], v[76:79]
	s_mov_b32 m0, s28
	v_lshl_add_u64 v[194:195], s[18:19], 0, v[158:159]
	global_load_lds_dwordx4 v[194:195], off
	v_mfma_f32_16x16x32_bf16 v[72:75], v[136:139], v[186:189], v[72:75]
	v_mfma_f32_16x16x32_bf16 v[124:127], v[132:135], v[148:151], v[124:127]
	v_mfma_f32_16x16x32_bf16 v[120:123], v[140:143], v[148:151], v[120:123]
	v_mfma_f32_16x16x32_bf16 v[108:111], v[132:135], v[174:177], v[108:111]
	v_mfma_f32_16x16x32_bf16 v[104:107], v[140:143], v[174:177], v[104:107]
	v_mfma_f32_16x16x32_bf16 v[92:95], v[132:135], v[182:185], v[92:95]
	v_mfma_f32_16x16x32_bf16 v[88:91], v[140:143], v[182:185], v[88:91]
	v_mfma_f32_16x16x32_bf16 v[76:79], v[132:135], v[190:193], v[76:79]
	s_setprio 0
	v_mfma_f32_16x16x32_bf16 v[72:75], v[140:143], v[190:193], v[72:75]
	s_barrier
	s_add_i32 s40, 0, 0x1c000
	s_add_u32 s18, s14, 0x4000
	s_addc_u32 s19, s15, 0
	s_add_i32 s39, s39, s23
	v_add_u32_e32 v152, s40, v170
	v_lshl_add_u64 v[210:211], s[18:19], 0, v[156:157]
	s_mov_b32 m0, s39
	ds_read_b128 v[194:197], v152
	ds_read_b128 v[198:201], v152 offset:1024
	ds_read_b128 v[202:205], v152 offset:2048
	ds_read_b128 v[206:209], v152 offset:3072
	global_load_lds_dwordx4 v[210:211], off
	s_add_i32 m0, s39, 0x2000
	v_lshl_add_u64 v[210:211], s[18:19], 0, v[158:159]
	global_load_lds_dwordx4 v[210:211], off
	s_barrier
	s_waitcnt lgkmcnt(0)
	v_mfma_f32_16x16x32_bf16 v[116:119], v[194:197], v[144:147], v[116:119]
	s_setprio 1
	v_mfma_f32_16x16x32_bf16 v[112:115], v[202:205], v[144:147], v[112:115]
	s_mov_b32 m0, s29
	v_lshl_add_u64 v[210:211], s[16:17], 0, v[156:157]
	v_mfma_f32_16x16x32_bf16 v[100:103], v[194:197], v[166:169], v[100:103]
	v_mfma_f32_16x16x32_bf16 v[96:99], v[202:205], v[166:169], v[96:99]
	v_mfma_f32_16x16x32_bf16 v[84:87], v[194:197], v[178:181], v[84:87]
	v_mfma_f32_16x16x32_bf16 v[80:83], v[202:205], v[178:181], v[80:83]
	v_mfma_f32_16x16x32_bf16 v[68:71], v[194:197], v[186:189], v[68:71]
	v_mfma_f32_16x16x32_bf16 v[64:67], v[202:205], v[186:189], v[64:67]
	v_mfma_f32_16x16x32_bf16 v[116:119], v[198:201], v[148:151], v[116:119]
	v_mfma_f32_16x16x32_bf16 v[112:115], v[206:209], v[148:151], v[112:115]
	v_mfma_f32_16x16x32_bf16 v[100:103], v[198:201], v[174:177], v[100:103]
	v_mfma_f32_16x16x32_bf16 v[96:99], v[206:209], v[174:177], v[96:99]
	v_mfma_f32_16x16x32_bf16 v[84:87], v[198:201], v[182:185], v[84:87]
	v_mfma_f32_16x16x32_bf16 v[80:83], v[206:209], v[182:185], v[80:83]
	v_mfma_f32_16x16x32_bf16 v[68:71], v[198:201], v[190:193], v[68:71]
	s_setprio 0
	v_mfma_f32_16x16x32_bf16 v[64:67], v[206:209], v[190:193], v[64:67]
	s_barrier
	ds_read_b128 v[144:147], v172 offset:49152
	ds_read_b128 v[148:151], v172 offset:50176
	ds_read_b128 v[166:169], v172 offset:51200
	ds_read_b128 v[174:177], v172 offset:52224
	ds_read_b128 v[178:181], v172 offset:53248
	ds_read_b128 v[182:185], v172 offset:54272
	ds_read_b128 v[186:189], v172 offset:55296
	ds_read_b128 v[190:193], v172 offset:56320
	global_load_lds_dwordx4 v[210:211], off
	s_mov_b32 m0, s30
	v_lshl_add_u64 v[210:211], s[16:17], 0, v[158:159]
	global_load_lds_dwordx4 v[210:211], off
	s_barrier
; #define PG8_STAGE(bufoff, gbase, voff) do { _Pragma("unroll") for (int _i = 0; _i < 2; ++_i) \
;         __builtin_amdgcn_global_load_lds((const unsigned*)((const char*)(gbase) + (voff)[_i]), (LAS unsigned*)(lds + (bufoff) + ldsw + _i * 8192), 16, 0, 0); } while (0)
; #define PG8_LDA(dst, b, h) do { _Pragma("unroll") for (int m = 0; m < 4; ++m) _Pragma("unroll") for (int k = 0; k < 2; ++k) dst[m][k] = *(const LAS bf16x8*)(lds + PG8_SA(b, h) + aoff + m * 2048 + k * 1024); } while (0)
; #define PG8_WAIT_V(n) asm volatile("s_waitcnt vmcnt(" #n ")" ::: "memory")
; #define PG8_WAIT_L(n) asm volatile("s_waitcnt lgkmcnt(" #n ")" ::: "memory")
; template <class Epi>
; __device__ __forceinline__ void gemm_phase(LAS unsigned char* lds, const Gemm g, const StaticOrder& S, const Epi& E) {
;     ...
;         for (int t = 0; t < nt; t += 2) {
;             const bool last = (t == nt - 2);
;             const char* a1 = cA + (size_t)(t + 1) * kstep;
;             const char* a2 = last ? nA : cA + (size_t)(t + 2) * kstep; const char* b2 = last ? nB : cB + (size_t)(t + 2) * kstep;
;             const char* a3 = a2 + kstep; const char* b3 = b2 + kstep;
;             PG8_LDB(B0, 0, 0); PG8_SCHED; PG8_LDA(At, 0, 0); PG8_STAGE(PG8_SA(1, 1), a1 + hstepA, voffA);
;             PG8_WAIT_L(8); PG8_BAR; PG8_WAIT_L(0); PG8_MMA(0, 0, At, B0); PG8_BAR; PG8_SCHED;
;             PG8_LDB(B1, 0, 1); PG8_STAGE(PG8_SB(0, 0), b2, voffB);
;             PG8_BAR; PG8_WAIT_L(0); PG8_MMA(0, 1, At, B1); PG8_BAR;
;             PG8_LDA(At, 0, 1); PG8_STAGE(PG8_SA(0, 0), a2, voffA);
;             PG8_BAR; PG8_WAIT_L(0); PG8_MMA(1, 0, At, B0); PG8_BAR; PG8_SCHED;
;             PG8_STAGE(PG8_SB(0, 1), b2 + hstepB, voffB);
;             PG8_WAIT_V(6); PG8_BAR; PG8_MMA(1, 1, At, B1); PG8_BAR;
;             PG8_LDB(B0, 1, 0); PG8_SCHED; PG8_LDA(At, 1, 0); PG8_STAGE(PG8_SA(0, 1), a2 + hstepA, voffA);
;             PG8_WAIT_L(8); PG8_BAR; PG8_WAIT_L(0); PG8_MMA(0, 0, At, B0); PG8_BAR; PG8_SCHED;
;             PG8_LDB(B1, 1, 1); PG8_STAGE(PG8_SB(1, 0), b3, voffB);
;             PG8_BAR; PG8_WAIT_L(0); PG8_MMA(0, 1, At, B1); PG8_BAR;
;             PG8_LDA(At, 1, 1); PG8_STAGE(PG8_SA(1, 0), a3, voffA);
;             PG8_BAR; PG8_WAIT_L(0); PG8_MMA(1, 0, At, B0); PG8_BAR; PG8_SCHED;
;             PG8_STAGE(PG8_SB(1, 1), b3 + hstepB, voffB);
;             PG8_WAIT_V(6); PG8_BAR; PG8_MMA(1, 1, At, B1); PG8_BAR;
	s_waitcnt lgkmcnt(0)
	v_mfma_f32_16x16x32_bf16 v[60:63], v[128:131], v[144:147], v[60:63]
	s_setprio 1
	v_mfma_f32_16x16x32_bf16 v[56:59], v[136:139], v[144:147], v[56:59]
	v_mfma_f32_16x16x32_bf16 v[44:47], v[128:131], v[166:169], v[44:47]
	v_mfma_f32_16x16x32_bf16 v[40:43], v[136:139], v[166:169], v[40:43]
	v_mfma_f32_16x16x32_bf16 v[28:31], v[128:131], v[178:181], v[28:31]
	v_mfma_f32_16x16x32_bf16 v[24:27], v[136:139], v[178:181], v[24:27]
	v_mfma_f32_16x16x32_bf16 v[12:15], v[128:131], v[186:189], v[12:15]
	v_mfma_f32_16x16x32_bf16 v[8:11], v[136:139], v[186:189], v[8:11]
	v_mfma_f32_16x16x32_bf16 v[60:63], v[132:135], v[148:151], v[60:63]
	v_mfma_f32_16x16x32_bf16 v[56:59], v[140:143], v[148:151], v[56:59]
	v_mfma_f32_16x16x32_bf16 v[44:47], v[132:135], v[174:177], v[44:47]
	v_mfma_f32_16x16x32_bf16 v[40:43], v[140:143], v[174:177], v[40:43]
	v_mfma_f32_16x16x32_bf16 v[28:31], v[132:135], v[182:185], v[28:31]
	v_mfma_f32_16x16x32_bf16 v[24:27], v[140:143], v[182:185], v[24:27]
	v_mfma_f32_16x16x32_bf16 v[12:15], v[132:135], v[190:193], v[12:15]
	s_setprio 0
	v_mfma_f32_16x16x32_bf16 v[8:11], v[140:143], v[190:193], v[8:11]
	s_barrier
	s_add_u32 s14, s14, 0x84000
	s_addc_u32 s15, s15, 0
	s_add_i32 s16, s40, s23
	s_mov_b32 m0, s16
	v_lshl_add_u64 v[128:129], s[14:15], 0, v[156:157]
	global_load_lds_dwordx4 v[128:129], off
	s_add_i32 m0, s16, 0x2000
	v_lshl_add_u64 v[128:129], s[14:15], 0, v[158:159]
	global_load_lds_dwordx4 v[128:129], off
	s_waitcnt vmcnt(6)
	s_barrier
	v_mfma_f32_16x16x32_bf16 v[52:55], v[194:197], v[144:147], v[52:55]
	s_setprio 1
	v_mfma_f32_16x16x32_bf16 v[48:51], v[202:205], v[144:147], v[48:51]
	s_add_i32 s38, s38, 2
	s_add_u32 s12, s12, 0x8000
	s_addc_u32 s13, s13, 0
	s_add_u32 s36, s36, 0x8000
	s_addc_u32 s37, s37, 0
	v_mfma_f32_16x16x32_bf16 v[36:39], v[194:197], v[166:169], v[36:39]
	v_mfma_f32_16x16x32_bf16 v[32:35], v[202:205], v[166:169], v[32:35]
	v_mfma_f32_16x16x32_bf16 v[20:23], v[194:197], v[178:181], v[20:23]
	v_mfma_f32_16x16x32_bf16 v[16:19], v[202:205], v[178:181], v[16:19]
	v_mfma_f32_16x16x32_bf16 v[4:7], v[194:197], v[186:189], v[4:7]
	v_mfma_f32_16x16x32_bf16 v[0:3], v[202:205], v[186:189], v[0:3]
	v_mfma_f32_16x16x32_bf16 v[52:55], v[198:201], v[148:151], v[52:55]
	v_mfma_f32_16x16x32_bf16 v[48:51], v[206:209], v[148:151], v[48:51]
	v_mfma_f32_16x16x32_bf16 v[36:39], v[198:201], v[174:177], v[36:39]
	v_mfma_f32_16x16x32_bf16 v[32:35], v[206:209], v[174:177], v[32:35]
	v_mfma_f32_16x16x32_bf16 v[20:23], v[198:201], v[182:185], v[20:23]
	v_mfma_f32_16x16x32_bf16 v[16:19], v[206:209], v[182:185], v[16:19]
	v_mfma_f32_16x16x32_bf16 v[4:7], v[198:201], v[190:193], v[4:7]
	s_cmp_gt_u32 s38, 29
	s_setprio 0
	v_mfma_f32_16x16x32_bf16 v[0:3], v[206:209], v[190:193], v[0:3]
	s_barrier
	s_cbranch_scc0 .LBB0_247
	s_branch .Lpeel_done_247
.LBB0_247:
	s_add_u32 s14, s12, 0xfff84000
	s_addc_u32 s15, s13, -1
	s_cmp_eq_u32 s38, 28
	s_cselect_b32 s18, s11, s14
	s_cselect_b32 s19, s5, s15
	s_cselect_b32 s14, s35, s36
	s_cselect_b32 s15, s3, s37
	s_add_u32 s16, s18, 0x4000
	s_addc_u32 s17, s19, 0
	s_add_i32 s39, 0, 0x10000
	v_add_u32_e32 v140, s39, v170
	ds_read_b128 v[128:131], v140
	ds_read_b128 v[132:135], v140 offset:1024
	ds_read_b128 v[136:139], v140 offset:2048
	ds_read_b128 v[140:143], v140 offset:3072
	ds_read_b128 v[144:147], v172
	ds_read_b128 v[148:151], v172 offset:1024
	ds_read_b128 v[166:169], v172 offset:2048
	ds_read_b128 v[174:177], v172 offset:3072
	ds_read_b128 v[178:181], v172 offset:4096
	ds_read_b128 v[182:185], v172 offset:5120
	ds_read_b128 v[186:189], v172 offset:6144
	ds_read_b128 v[190:193], v172 offset:7168
	s_waitcnt lgkmcnt(8)
	s_barrier
	s_waitcnt lgkmcnt(0)
	v_mfma_f32_16x16x32_bf16 v[124:127], v[128:131], v[144:147], v[124:127]
	s_setprio 1
	v_mfma_f32_16x16x32_bf16 v[120:123], v[136:139], v[144:147], v[120:123]
	v_mfma_f32_16x16x32_bf16 v[108:111], v[128:131], v[166:169], v[108:111]
	s_add_i32 m0, s25, 0xc000
	v_lshl_add_u64 v[194:195], s[12:13], 0, v[156:157]
	global_load_lds_dwordx4 v[194:195], off
	v_mfma_f32_16x16x32_bf16 v[104:107], v[136:139], v[166:169], v[104:107]
	v_mfma_f32_16x16x32_bf16 v[92:95], v[128:131], v[178:181], v[92:95]
	v_mfma_f32_16x16x32_bf16 v[88:91], v[136:139], v[178:181], v[88:91]
	v_mfma_f32_16x16x32_bf16 v[76:79], v[128:131], v[186:189], v[76:79]
	s_add_i32 m0, s25, 0xe000
	v_lshl_add_u64 v[194:195], s[12:13], 0, v[158:159]
	global_load_lds_dwordx4 v[194:195], off
	v_mfma_f32_16x16x32_bf16 v[72:75], v[136:139], v[186:189], v[72:75]
	v_mfma_f32_16x16x32_bf16 v[124:127], v[132:135], v[148:151], v[124:127]
	v_mfma_f32_16x16x32_bf16 v[120:123], v[140:143], v[148:151], v[120:123]
	v_mfma_f32_16x16x32_bf16 v[108:111], v[132:135], v[174:177], v[108:111]
	v_mfma_f32_16x16x32_bf16 v[104:107], v[140:143], v[174:177], v[104:107]
	v_mfma_f32_16x16x32_bf16 v[92:95], v[132:135], v[182:185], v[92:95]
	v_mfma_f32_16x16x32_bf16 v[88:91], v[140:143], v[182:185], v[88:91]
	v_mfma_f32_16x16x32_bf16 v[76:79], v[132:135], v[190:193], v[76:79]
	s_setprio 0
	v_mfma_f32_16x16x32_bf16 v[72:75], v[140:143], v[190:193], v[72:75]
	s_barrier
	s_add_i32 s42, 0, 0x14000
	s_add_i32 s39, s39, s23
	v_add_u32_e32 v152, s42, v170
	v_lshl_add_u64 v[210:211], s[14:15], 0, v[156:157]
	s_mov_b32 m0, s39
	ds_read_b128 v[194:197], v152
	ds_read_b128 v[198:201], v152 offset:1024
	ds_read_b128 v[202:205], v152 offset:2048
	ds_read_b128 v[206:209], v152 offset:3072
	global_load_lds_dwordx4 v[210:211], off
	s_add_i32 m0, s39, 0x2000
	v_lshl_add_u64 v[210:211], s[14:15], 0, v[158:159]
	global_load_lds_dwordx4 v[210:211], off
	s_barrier
; #define PG8_STAGE(bufoff, gbase, voff) do { _Pragma("unroll") for (int _i = 0; _i < 2; ++_i) \
;         __builtin_amdgcn_global_load_lds((const unsigned*)((const char*)(gbase) + (voff)[_i]), (LAS unsigned*)(lds + (bufoff) + ldsw + _i * 8192), 16, 0, 0); } while (0)
; #define PG8_LDA(dst, b, h) do { _Pragma("unroll") for (int m = 0; m < 4; ++m) _Pragma("unroll") for (int k = 0; k < 2; ++k) dst[m][k] = *(const LAS bf16x8*)(lds + PG8_SA(b, h) + aoff + m * 2048 + k * 1024); } while (0)
; #define PG8_LDB(dst, b, h) do { _Pragma("unroll") for (int n = 0; n < 2; ++n) _Pragma("unroll") for (int k = 0; k < 2; ++k) dst[n][k] = *(const LAS bf16x8*)(lds + PG8_SB(b, h) + boff + n * 2048 + k * 1024); } while (0)
; #define PG8_MMA(ai, bj, At, Bt) do { __builtin_amdgcn_s_setprio(1); _Pragma("unroll") for (int m = 0; m < 4; ++m) _Pragma("unroll") for (int n = 0; n < 2; ++n) _Pragma("unroll") for (int k = 0; k < 2; ++k) \
;         acc[ai][bj][m][n] = __builtin_amdgcn_mfma_f32_16x16x32_bf16(Bt[n][k], At[m][k], acc[ai][bj][m][n], 0, 0, 0); __builtin_amdgcn_s_setprio(0); } while (0)
; #define PG8_WAIT_V(n) asm volatile("s_waitcnt vmcnt(" #n ")" ::: "memory")
; #define PG8_WAIT_L(n) asm volatile("s_waitcnt lgkmcnt(" #n ")" ::: "memory")
; #define PG8_BAR __builtin_amdgcn_s_barrier()
; #define PG8_SCHED __builtin_amdgcn_sched_barrier(0)
; template <class Epi>
; __device__ __forceinline__ void gemm_phase(LAS unsigned char* lds, const Gemm g, const StaticOrder& S, const Epi& E) {
;     ...
;             PG8_BAR; PG8_WAIT_L(0); PG8_MMA(0, 1, At, B1); PG8_BAR;
;             PG8_LDA(At, 0, 1); PG8_STAGE(PG8_SA(0, 0), a2, voffA);
;             PG8_BAR; PG8_WAIT_L(0); PG8_MMA(1, 0, At, B0); PG8_BAR; PG8_SCHED;
;             PG8_STAGE(PG8_SB(0, 1), b2 + hstepB, voffB);
;             PG8_WAIT_V(6); PG8_BAR; PG8_MMA(1, 1, At, B1); PG8_BAR;
;             PG8_LDB(B0, 1, 0); PG8_SCHED; PG8_LDA(At, 1, 0); PG8_STAGE(PG8_SA(0, 1), a2 + hstepA, voffA);
	s_waitcnt lgkmcnt(0)
	v_mfma_f32_16x16x32_bf16 v[116:119], v[194:197], v[144:147], v[116:119]
	s_setprio 1
	v_mfma_f32_16x16x32_bf16 v[112:115], v[202:205], v[144:147], v[112:115]
	s_mov_b32 m0, s25
	v_lshl_add_u64 v[210:211], s[18:19], 0, v[156:157]
	v_mfma_f32_16x16x32_bf16 v[100:103], v[194:197], v[166:169], v[100:103]
	v_mfma_f32_16x16x32_bf16 v[96:99], v[202:205], v[166:169], v[96:99]
	v_mfma_f32_16x16x32_bf16 v[84:87], v[194:197], v[178:181], v[84:87]
	v_mfma_f32_16x16x32_bf16 v[80:83], v[202:205], v[178:181], v[80:83]
	v_mfma_f32_16x16x32_bf16 v[68:71], v[194:197], v[186:189], v[68:71]
	v_mfma_f32_16x16x32_bf16 v[64:67], v[202:205], v[186:189], v[64:67]
	v_mfma_f32_16x16x32_bf16 v[116:119], v[198:201], v[148:151], v[116:119]
	v_mfma_f32_16x16x32_bf16 v[112:115], v[206:209], v[148:151], v[112:115]
	v_mfma_f32_16x16x32_bf16 v[100:103], v[198:201], v[174:177], v[100:103]
	v_mfma_f32_16x16x32_bf16 v[96:99], v[206:209], v[174:177], v[96:99]
	v_mfma_f32_16x16x32_bf16 v[84:87], v[198:201], v[182:185], v[84:87]
	v_mfma_f32_16x16x32_bf16 v[80:83], v[206:209], v[182:185], v[80:83]
	v_mfma_f32_16x16x32_bf16 v[68:71], v[198:201], v[190:193], v[68:71]
	s_setprio 0
	v_mfma_f32_16x16x32_bf16 v[64:67], v[206:209], v[190:193], v[64:67]
	s_barrier
	ds_read_b128 v[144:147], v172 offset:16384
	ds_read_b128 v[148:151], v172 offset:17408
	ds_read_b128 v[166:169], v172 offset:18432
	ds_read_b128 v[174:177], v172 offset:19456
	ds_read_b128 v[178:181], v172 offset:20480
	ds_read_b128 v[182:185], v172 offset:21504
	ds_read_b128 v[186:189], v172 offset:22528
	ds_read_b128 v[190:193], v172 offset:23552
	global_load_lds_dwordx4 v[210:211], off
	s_mov_b32 m0, s26
	v_lshl_add_u64 v[210:211], s[18:19], 0, v[158:159]
	global_load_lds_dwordx4 v[210:211], off
	s_barrier
	s_waitcnt lgkmcnt(0)
	v_mfma_f32_16x16x32_bf16 v[60:63], v[128:131], v[144:147], v[60:63]
	s_setprio 1
	v_mfma_f32_16x16x32_bf16 v[56:59], v[136:139], v[144:147], v[56:59]
	v_mfma_f32_16x16x32_bf16 v[44:47], v[128:131], v[166:169], v[44:47]
	v_mfma_f32_16x16x32_bf16 v[40:43], v[136:139], v[166:169], v[40:43]
	v_mfma_f32_16x16x32_bf16 v[28:31], v[128:131], v[178:181], v[28:31]
	v_mfma_f32_16x16x32_bf16 v[24:27], v[136:139], v[178:181], v[24:27]
	v_mfma_f32_16x16x32_bf16 v[12:15], v[128:131], v[186:189], v[12:15]
	v_mfma_f32_16x16x32_bf16 v[8:11], v[136:139], v[186:189], v[8:11]
	v_mfma_f32_16x16x32_bf16 v[60:63], v[132:135], v[148:151], v[60:63]
	v_mfma_f32_16x16x32_bf16 v[56:59], v[140:143], v[148:151], v[56:59]
	v_mfma_f32_16x16x32_bf16 v[44:47], v[132:135], v[174:177], v[44:47]
	v_mfma_f32_16x16x32_bf16 v[40:43], v[140:143], v[174:177], v[40:43]
	v_mfma_f32_16x16x32_bf16 v[28:31], v[132:135], v[182:185], v[28:31]
	v_mfma_f32_16x16x32_bf16 v[24:27], v[140:143], v[182:185], v[24:27]
	v_mfma_f32_16x16x32_bf16 v[12:15], v[132:135], v[190:193], v[12:15]
	s_setprio 0
	v_mfma_f32_16x16x32_bf16 v[8:11], v[140:143], v[190:193], v[8:11]
	s_barrier
	s_add_u32 s40, s14, 0x80000
	s_addc_u32 s41, s15, 0
	s_add_i32 s39, s42, s23
	s_mov_b32 m0, s39
	v_lshl_add_u64 v[128:129], s[40:41], 0, v[156:157]
	global_load_lds_dwordx4 v[128:129], off
	s_add_i32 m0, s39, 0x2000
	v_lshl_add_u64 v[128:129], s[40:41], 0, v[158:159]
	global_load_lds_dwordx4 v[128:129], off
	s_waitcnt vmcnt(6)
	s_barrier
	v_mfma_f32_16x16x32_bf16 v[52:55], v[194:197], v[144:147], v[52:55]
	s_setprio 1
	v_mfma_f32_16x16x32_bf16 v[48:51], v[202:205], v[144:147], v[48:51]
	s_add_i32 s39, 0, 0x18000
	v_add_u32_e32 v140, s39, v170
	v_mfma_f32_16x16x32_bf16 v[36:39], v[194:197], v[166:169], v[36:39]
	v_mfma_f32_16x16x32_bf16 v[32:35], v[202:205], v[166:169], v[32:35]
	v_mfma_f32_16x16x32_bf16 v[20:23], v[194:197], v[178:181], v[20:23]
	v_mfma_f32_16x16x32_bf16 v[16:19], v[202:205], v[178:181], v[16:19]
	v_mfma_f32_16x16x32_bf16 v[4:7], v[194:197], v[186:189], v[4:7]
	v_mfma_f32_16x16x32_bf16 v[0:3], v[202:205], v[186:189], v[0:3]
	v_mfma_f32_16x16x32_bf16 v[52:55], v[198:201], v[148:151], v[52:55]
	v_mfma_f32_16x16x32_bf16 v[48:51], v[206:209], v[148:151], v[48:51]
	v_mfma_f32_16x16x32_bf16 v[36:39], v[198:201], v[174:177], v[36:39]
	v_mfma_f32_16x16x32_bf16 v[32:35], v[206:209], v[174:177], v[32:35]
	v_mfma_f32_16x16x32_bf16 v[20:23], v[198:201], v[182:185], v[20:23]
	v_mfma_f32_16x16x32_bf16 v[16:19], v[206:209], v[182:185], v[16:19]
	v_mfma_f32_16x16x32_bf16 v[4:7], v[198:201], v[190:193], v[4:7]
	s_setprio 0
	v_mfma_f32_16x16x32_bf16 v[0:3], v[206:209], v[190:193], v[0:3]
	s_barrier
	ds_read_b128 v[128:131], v140
	ds_read_b128 v[132:135], v140 offset:1024
	ds_read_b128 v[136:139], v140 offset:2048
	ds_read_b128 v[140:143], v140 offset:3072
	s_add_u32 s18, s18, 0x80000
	s_addc_u32 s19, s19, 0
	ds_read_b128 v[144:147], v172 offset:32768
	ds_read_b128 v[148:151], v172 offset:33792
	ds_read_b128 v[166:169], v172 offset:34816
	ds_read_b128 v[174:177], v172 offset:35840
	ds_read_b128 v[178:181], v172 offset:36864
	ds_read_b128 v[182:185], v172 offset:37888
	ds_read_b128 v[186:189], v172 offset:38912
	ds_read_b128 v[190:193], v172 offset:39936
	s_waitcnt lgkmcnt(8)
	s_barrier
; #define PG8_STAGE(bufoff, gbase, voff) do { _Pragma("unroll") for (int _i = 0; _i < 2; ++_i) \
;         __builtin_amdgcn_global_load_lds((const unsigned*)((const char*)(gbase) + (voff)[_i]), (LAS unsigned*)(lds + (bufoff) + ldsw + _i * 8192), 16, 0, 0); } while (0)
; #define PG8_LDA(dst, b, h) do { _Pragma("unroll") for (int m = 0; m < 4; ++m) _Pragma("unroll") for (int k = 0; k < 2; ++k) dst[m][k] = *(const LAS bf16x8*)(lds + PG8_SA(b, h) + aoff + m * 2048 + k * 1024); } while (0)
; #define PG8_LDB(dst, b, h) do { _Pragma("unroll") for (int n = 0; n < 2; ++n) _Pragma("unroll") for (int k = 0; k < 2; ++k) dst[n][k] = *(const LAS bf16x8*)(lds + PG8_SB(b, h) + boff + n * 2048 + k * 1024); } while (0)
; #define PG8_MMA(ai, bj, At, Bt) do { __builtin_amdgcn_s_setprio(1); _Pragma("unroll") for (int m = 0; m < 4; ++m) _Pragma("unroll") for (int n = 0; n < 2; ++n) _Pragma("unroll") for (int k = 0; k < 2; ++k) \
;         acc[ai][bj][m][n] = __builtin_amdgcn_mfma_f32_16x16x32_bf16(Bt[n][k], At[m][k], acc[ai][bj][m][n], 0, 0, 0); __builtin_amdgcn_s_setprio(0); } while (0)
; #define PG8_WAIT_V(n) asm volatile("s_waitcnt vmcnt(" #n ")" ::: "memory")
; #define PG8_WAIT_L(n) asm volatile("s_waitcnt lgkmcnt(" #n ")" ::: "memory")
; #define PG8_BAR __builtin_amdgcn_s_barrier()
; #define PG8_SCHED __builtin_amdgcn_sched_barrier(0)
; template <class Epi>
; __device__ __forceinline__ void gemm_phase(LAS unsigned char* lds, const Gemm g, const StaticOrder& S, const Epi& E) {
;     ...
;             PG8_WAIT_L(8); PG8_BAR; PG8_WAIT_L(0); PG8_MMA(0, 0, At, B0); PG8_BAR; PG8_SCHED;
;             PG8_LDB(B1, 1, 1); PG8_STAGE(PG8_SB(1, 0), b3, voffB);
;             PG8_BAR; PG8_WAIT_L(0); PG8_MMA(0, 1, At, B1); PG8_BAR;
;             PG8_LDA(At, 1, 1); PG8_STAGE(PG8_SA(1, 0), a3, voffA);
;             PG8_BAR; PG8_WAIT_L(0); PG8_MMA(1, 0, At, B0); PG8_BAR; PG8_SCHED;
;             PG8_STAGE(PG8_SB(1, 1), b3 + hstepB, voffB);
;             PG8_WAIT_V(6); PG8_BAR; PG8_MMA(1, 1, At, B1); PG8_BAR;
	s_waitcnt lgkmcnt(0)
	v_mfma_f32_16x16x32_bf16 v[124:127], v[128:131], v[144:147], v[124:127]
	s_setprio 1
	v_mfma_f32_16x16x32_bf16 v[120:123], v[136:139], v[144:147], v[120:123]
	v_mfma_f32_16x16x32_bf16 v[108:111], v[128:131], v[166:169], v[108:111]
	s_mov_b32 m0, s27
	v_lshl_add_u64 v[194:195], s[18:19], 0, v[156:157]
	global_load_lds_dwordx4 v[194:195], off
	v_mfma_f32_16x16x32_bf16 v[104:107], v[136:139], v[166:169], v[104:107]
	v_mfma_f32_16x16x32_bf16 v[92:95], v[128:131], v[178:181], v[92:95]
	v_mfma_f32_16x16x32_bf16 v[88:91], v[136:139], v[178:181], v[88:91]
	v_mfma_f32_16x16x32_bf16 v[76:79], v[128:131], v[186:189], v[76:79]
	s_mov_b32 m0, s28
	v_lshl_add_u64 v[194:195], s[18:19], 0, v[158:159]
	global_load_lds_dwordx4 v[194:195], off
	v_mfma_f32_16x16x32_bf16 v[72:75], v[136:139], v[186:189], v[72:75]
	v_mfma_f32_16x16x32_bf16 v[124:127], v[132:135], v[148:151], v[124:127]
	v_mfma_f32_16x16x32_bf16 v[120:123], v[140:143], v[148:151], v[120:123]
	v_mfma_f32_16x16x32_bf16 v[108:111], v[132:135], v[174:177], v[108:111]
	v_mfma_f32_16x16x32_bf16 v[104:107], v[140:143], v[174:177], v[104:107]
	v_mfma_f32_16x16x32_bf16 v[92:95], v[132:135], v[182:185], v[92:95]
	v_mfma_f32_16x16x32_bf16 v[88:91], v[140:143], v[182:185], v[88:91]
	v_mfma_f32_16x16x32_bf16 v[76:79], v[132:135], v[190:193], v[76:79]
	s_setprio 0
	v_mfma_f32_16x16x32_bf16 v[72:75], v[140:143], v[190:193], v[72:75]
	s_barrier
	s_add_i32 s40, 0, 0x1c000
	s_add_u32 s18, s14, 0x4000
	s_addc_u32 s19, s15, 0
	s_add_i32 s39, s39, s23
	v_add_u32_e32 v152, s40, v170
	v_lshl_add_u64 v[210:211], s[18:19], 0, v[156:157]
	s_mov_b32 m0, s39
	ds_read_b128 v[194:197], v152
	ds_read_b128 v[198:201], v152 offset:1024
	ds_read_b128 v[202:205], v152 offset:2048
	ds_read_b128 v[206:209], v152 offset:3072
	global_load_lds_dwordx4 v[210:211], off
	s_add_i32 m0, s39, 0x2000
	v_lshl_add_u64 v[210:211], s[18:19], 0, v[158:159]
	global_load_lds_dwordx4 v[210:211], off
	s_barrier
	s_waitcnt lgkmcnt(0)
	v_mfma_f32_16x16x32_bf16 v[116:119], v[194:197], v[144:147], v[116:119]
	s_setprio 1
	v_mfma_f32_16x16x32_bf16 v[112:115], v[202:205], v[144:147], v[112:115]
	s_mov_b32 m0, s29
	v_lshl_add_u64 v[210:211], s[16:17], 0, v[156:157]
	v_mfma_f32_16x16x32_bf16 v[100:103], v[194:197], v[166:169], v[100:103]
	v_mfma_f32_16x16x32_bf16 v[96:99], v[202:205], v[166:169], v[96:99]
	v_mfma_f32_16x16x32_bf16 v[84:87], v[194:197], v[178:181], v[84:87]
	v_mfma_f32_16x16x32_bf16 v[80:83], v[202:205], v[178:181], v[80:83]
	v_mfma_f32_16x16x32_bf16 v[68:71], v[194:197], v[186:189], v[68:71]
	v_mfma_f32_16x16x32_bf16 v[64:67], v[202:205], v[186:189], v[64:67]
	v_mfma_f32_16x16x32_bf16 v[116:119], v[198:201], v[148:151], v[116:119]
	v_mfma_f32_16x16x32_bf16 v[112:115], v[206:209], v[148:151], v[112:115]
	v_mfma_f32_16x16x32_bf16 v[100:103], v[198:201], v[174:177], v[100:103]
	v_mfma_f32_16x16x32_bf16 v[96:99], v[206:209], v[174:177], v[96:99]
	v_mfma_f32_16x16x32_bf16 v[84:87], v[198:201], v[182:185], v[84:87]
	v_mfma_f32_16x16x32_bf16 v[80:83], v[206:209], v[182:185], v[80:83]
	v_mfma_f32_16x16x32_bf16 v[68:71], v[198:201], v[190:193], v[68:71]
	s_setprio 0
	v_mfma_f32_16x16x32_bf16 v[64:67], v[206:209], v[190:193], v[64:67]
	s_barrier
	ds_read_b128 v[144:147], v172 offset:49152
	ds_read_b128 v[148:151], v172 offset:50176
	ds_read_b128 v[166:169], v172 offset:51200
	ds_read_b128 v[174:177], v172 offset:52224
	ds_read_b128 v[178:181], v172 offset:53248
	ds_read_b128 v[182:185], v172 offset:54272
	ds_read_b128 v[186:189], v172 offset:55296
	ds_read_b128 v[190:193], v172 offset:56320
	global_load_lds_dwordx4 v[210:211], off
	s_mov_b32 m0, s30
	v_lshl_add_u64 v[210:211], s[16:17], 0, v[158:159]
	global_load_lds_dwordx4 v[210:211], off
	s_barrier
	s_waitcnt lgkmcnt(0)
	v_mfma_f32_16x16x32_bf16 v[60:63], v[128:131], v[144:147], v[60:63]
	s_setprio 1
	v_mfma_f32_16x16x32_bf16 v[56:59], v[136:139], v[144:147], v[56:59]
	v_mfma_f32_16x16x32_bf16 v[44:47], v[128:131], v[166:169], v[44:47]
	v_mfma_f32_16x16x32_bf16 v[40:43], v[136:139], v[166:169], v[40:43]
	v_mfma_f32_16x16x32_bf16 v[28:31], v[128:131], v[178:181], v[28:31]
	v_mfma_f32_16x16x32_bf16 v[24:27], v[136:139], v[178:181], v[24:27]
	v_mfma_f32_16x16x32_bf16 v[12:15], v[128:131], v[186:189], v[12:15]
	v_mfma_f32_16x16x32_bf16 v[8:11], v[136:139], v[186:189], v[8:11]
	v_mfma_f32_16x16x32_bf16 v[60:63], v[132:135], v[148:151], v[60:63]
	v_mfma_f32_16x16x32_bf16 v[56:59], v[140:143], v[148:151], v[56:59]
	v_mfma_f32_16x16x32_bf16 v[44:47], v[132:135], v[174:177], v[44:47]
	v_mfma_f32_16x16x32_bf16 v[40:43], v[140:143], v[174:177], v[40:43]
	v_mfma_f32_16x16x32_bf16 v[28:31], v[132:135], v[182:185], v[28:31]
	v_mfma_f32_16x16x32_bf16 v[24:27], v[140:143], v[182:185], v[24:27]
	v_mfma_f32_16x16x32_bf16 v[12:15], v[132:135], v[190:193], v[12:15]
	s_setprio 0
	v_mfma_f32_16x16x32_bf16 v[8:11], v[140:143], v[190:193], v[8:11]
	s_barrier
	s_add_u32 s14, s14, 0x84000
	s_addc_u32 s15, s15, 0
	s_add_i32 s16, s40, s23
	s_mov_b32 m0, s16
	v_lshl_add_u64 v[128:129], s[14:15], 0, v[156:157]
	global_load_lds_dwordx4 v[128:129], off
	s_add_i32 m0, s16, 0x2000
	v_lshl_add_u64 v[128:129], s[14:15], 0, v[158:159]
	global_load_lds_dwordx4 v[128:129], off
	s_waitcnt vmcnt(6)
	s_barrier
	v_mfma_f32_16x16x32_bf16 v[52:55], v[194:197], v[144:147], v[52:55]
	s_setprio 1
	v_mfma_f32_16x16x32_bf16 v[48:51], v[202:205], v[144:147], v[48:51]
	s_add_i32 s38, s38, 2
	s_add_u32 s12, s12, 0x8000
	s_addc_u32 s13, s13, 0
	s_add_u32 s36, s36, 0x8000
	s_addc_u32 s37, s37, 0
	v_mfma_f32_16x16x32_bf16 v[36:39], v[194:197], v[166:169], v[36:39]
	v_mfma_f32_16x16x32_bf16 v[32:35], v[202:205], v[166:169], v[32:35]
	v_mfma_f32_16x16x32_bf16 v[20:23], v[194:197], v[178:181], v[20:23]
	v_mfma_f32_16x16x32_bf16 v[16:19], v[202:205], v[178:181], v[16:19]
	v_mfma_f32_16x16x32_bf16 v[4:7], v[194:197], v[186:189], v[4:7]
	v_mfma_f32_16x16x32_bf16 v[0:3], v[202:205], v[186:189], v[0:3]
	v_mfma_f32_16x16x32_bf16 v[52:55], v[198:201], v[148:151], v[52:55]
	v_mfma_f32_16x16x32_bf16 v[48:51], v[206:209], v[148:151], v[48:51]
	v_mfma_f32_16x16x32_bf16 v[36:39], v[198:201], v[174:177], v[36:39]
	v_mfma_f32_16x16x32_bf16 v[32:35], v[206:209], v[174:177], v[32:35]
	v_mfma_f32_16x16x32_bf16 v[20:23], v[198:201], v[182:185], v[20:23]
	v_mfma_f32_16x16x32_bf16 v[16:19], v[206:209], v[182:185], v[16:19]
	v_mfma_f32_16x16x32_bf16 v[4:7], v[198:201], v[190:193], v[4:7]
	s_cmp_gt_u32 s38, 29
	s_setprio 0
	v_mfma_f32_16x16x32_bf16 v[0:3], v[206:209], v[190:193], v[0:3]
	s_barrier
	s_cbranch_scc0 .LBB0_247
